# saddr + MFMA snake order in K-loops: consecutive MFMAs share an operand tuple (same per-accumulator order, bit-identical)
# speedup vs baseline: 1.0093x; 1.0065x over previous
.LBB0_109:
	ds_read_b128 v[130:133], v158
	ds_read_b128 v[162:165], v158 offset:1024
	ds_read_b128 v[166:169], v158 offset:2048
	ds_read_b128 v[170:173], v158 offset:3072
	ds_read_b128 v[174:177], v159
	ds_read_b128 v[178:181], v159 offset:1024
	ds_read_b128 v[182:185], v159 offset:2048
	ds_read_b128 v[186:189], v159 offset:3072
	s_add_u32 s22, s20, 0xfff04000
	s_addc_u32 s23, s21, -1
	s_cmp_eq_u32 s46, 60
	s_cselect_b32 s26, s42, s22
	s_cselect_b32 s27, s15, s23
	s_cselect_b32 s24, s43, s44
	s_cselect_b32 s25, s13, s45
	s_add_u32 s22, s26, 0x4000
	s_addc_u32 s23, s27, 0
	s_add_i32 m0, s29, 0xc000
	ds_read_b128 v[190:193], v160
	ds_read_b128 v[194:197], v160 offset:1024
	ds_read_b128 v[198:201], v160 offset:2048
	ds_read_b128 v[202:205], v160 offset:3072
	ds_read_b128 v[206:209], v160 offset:4096
	ds_read_b128 v[210:213], v160 offset:5120
	ds_read_b128 v[214:217], v160 offset:6144
	ds_read_b128 v[218:221], v160 offset:7168
	global_load_lds_dwordx4 v146, s[20:21]
	s_add_i32 m0, s29, 0xe000
	s_nop 0
	global_load_lds_dwordx4 v148, s[20:21]
	s_waitcnt vmcnt(8)
	s_waitcnt lgkmcnt(0)
	s_barrier
	s_setprio 1
	s_waitcnt lgkmcnt(0)
	v_mfma_f32_16x16x32_bf16 v[62:65], v[130:133], v[190:193], v[62:65]
	v_mfma_f32_16x16x32_bf16 v[58:61], v[166:169], v[190:193], v[58:61]
	v_mfma_f32_16x16x32_bf16 v[50:53], v[166:169], v[198:201], v[50:53]
	v_mfma_f32_16x16x32_bf16 v[54:57], v[130:133], v[198:201], v[54:57]
	v_mfma_f32_16x16x32_bf16 v[46:49], v[130:133], v[206:209], v[46:49]
	v_mfma_f32_16x16x32_bf16 v[42:45], v[166:169], v[206:209], v[42:45]
	v_mfma_f32_16x16x32_bf16 v[34:37], v[166:169], v[214:217], v[34:37]
	v_mfma_f32_16x16x32_bf16 v[38:41], v[130:133], v[214:217], v[38:41]
	v_mfma_f32_16x16x32_bf16 v[62:65], v[162:165], v[194:197], v[62:65]
	v_mfma_f32_16x16x32_bf16 v[58:61], v[170:173], v[194:197], v[58:61]
	v_mfma_f32_16x16x32_bf16 v[50:53], v[170:173], v[202:205], v[50:53]
	v_mfma_f32_16x16x32_bf16 v[54:57], v[162:165], v[202:205], v[54:57]
	v_mfma_f32_16x16x32_bf16 v[46:49], v[162:165], v[210:213], v[46:49]
	v_mfma_f32_16x16x32_bf16 v[42:45], v[170:173], v[210:213], v[42:45]
	v_mfma_f32_16x16x32_bf16 v[34:37], v[170:173], v[218:221], v[34:37]
	v_mfma_f32_16x16x32_bf16 v[38:41], v[162:165], v[218:221], v[38:41]
	s_setprio 0
	s_setprio 1
	v_mfma_f32_16x16x32_bf16 v[126:129], v[174:177], v[190:193], v[126:129]
	v_mfma_f32_16x16x32_bf16 v[122:125], v[182:185], v[190:193], v[122:125]
	v_mfma_f32_16x16x32_bf16 v[114:117], v[182:185], v[198:201], v[114:117]
	v_mfma_f32_16x16x32_bf16 v[118:121], v[174:177], v[198:201], v[118:121]
	v_mfma_f32_16x16x32_bf16 v[110:113], v[174:177], v[206:209], v[110:113]
	v_mfma_f32_16x16x32_bf16 v[106:109], v[182:185], v[206:209], v[106:109]
	v_mfma_f32_16x16x32_bf16 v[98:101], v[182:185], v[214:217], v[98:101]
	v_mfma_f32_16x16x32_bf16 v[102:105], v[174:177], v[214:217], v[102:105]
	v_mfma_f32_16x16x32_bf16 v[126:129], v[178:181], v[194:197], v[126:129]
	v_mfma_f32_16x16x32_bf16 v[122:125], v[186:189], v[194:197], v[122:125]
	v_mfma_f32_16x16x32_bf16 v[114:117], v[186:189], v[202:205], v[114:117]
	v_mfma_f32_16x16x32_bf16 v[118:121], v[178:181], v[202:205], v[118:121]
	v_mfma_f32_16x16x32_bf16 v[110:113], v[178:181], v[210:213], v[110:113]
	v_mfma_f32_16x16x32_bf16 v[106:109], v[186:189], v[210:213], v[106:109]
	v_mfma_f32_16x16x32_bf16 v[98:101], v[186:189], v[218:221], v[98:101]
	v_mfma_f32_16x16x32_bf16 v[102:105], v[178:181], v[218:221], v[102:105]
	s_setprio 0
	s_barrier
	s_add_i32 s47, s36, s28
	s_mov_b32 m0, s47
	ds_read_b128 v[190:193], v160 offset:16384
	ds_read_b128 v[194:197], v160 offset:17408
	ds_read_b128 v[198:201], v160 offset:18432
	ds_read_b128 v[202:205], v160 offset:19456
	ds_read_b128 v[206:209], v160 offset:20480
	ds_read_b128 v[210:213], v160 offset:21504
	ds_read_b128 v[214:217], v160 offset:22528
	ds_read_b128 v[218:221], v160 offset:23552
	global_load_lds_dwordx4 v138, s[24:25]
	s_add_i32 m0, s47, 0x2000
	s_add_u32 s48, s24, 0x100000
	s_addc_u32 s49, s25, 0
	s_add_i32 s47, s37, s28
	global_load_lds_dwordx4 v134, s[24:25]
	s_mov_b32 m0, s47
	s_nop 0
	global_load_lds_dwordx4 v138, s[48:49]
	s_add_i32 m0, s47, 0x2000
	s_nop 0
	global_load_lds_dwordx4 v134, s[48:49]
	s_mov_b32 m0, s29
	s_nop 0
	global_load_lds_dwordx4 v140, s[26:27]
	s_mov_b32 m0, s30
	s_nop 0
	global_load_lds_dwordx4 v136, s[26:27]
	s_waitcnt vmcnt(8)
	s_waitcnt lgkmcnt(0)
	s_barrier
	s_setprio 1
	s_waitcnt lgkmcnt(0)
	v_mfma_f32_16x16x32_bf16 v[30:33], v[130:133], v[190:193], v[30:33]
	v_mfma_f32_16x16x32_bf16 v[26:29], v[166:169], v[190:193], v[26:29]
	v_mfma_f32_16x16x32_bf16 v[18:21], v[166:169], v[198:201], v[18:21]
	v_mfma_f32_16x16x32_bf16 v[22:25], v[130:133], v[198:201], v[22:25]
	v_mfma_f32_16x16x32_bf16 v[14:17], v[130:133], v[206:209], v[14:17]
	v_mfma_f32_16x16x32_bf16 v[10:13], v[166:169], v[206:209], v[10:13]
	v_mfma_f32_16x16x32_bf16 v[2:5], v[166:169], v[214:217], v[2:5]
	v_mfma_f32_16x16x32_bf16 v[6:9], v[130:133], v[214:217], v[6:9]
	v_mfma_f32_16x16x32_bf16 v[30:33], v[162:165], v[194:197], v[30:33]
	v_mfma_f32_16x16x32_bf16 v[26:29], v[170:173], v[194:197], v[26:29]
	v_mfma_f32_16x16x32_bf16 v[18:21], v[170:173], v[202:205], v[18:21]
	v_mfma_f32_16x16x32_bf16 v[22:25], v[162:165], v[202:205], v[22:25]
	v_mfma_f32_16x16x32_bf16 v[14:17], v[162:165], v[210:213], v[14:17]
	v_mfma_f32_16x16x32_bf16 v[10:13], v[170:173], v[210:213], v[10:13]
	v_mfma_f32_16x16x32_bf16 v[2:5], v[170:173], v[218:221], v[2:5]
	v_mfma_f32_16x16x32_bf16 v[6:9], v[162:165], v[218:221], v[6:9]
	s_setprio 0
	s_setprio 1
	v_mfma_f32_16x16x32_bf16 v[94:97], v[174:177], v[190:193], v[94:97]
	v_mfma_f32_16x16x32_bf16 v[90:93], v[182:185], v[190:193], v[90:93]
	v_mfma_f32_16x16x32_bf16 v[82:85], v[182:185], v[198:201], v[82:85]
	v_mfma_f32_16x16x32_bf16 v[86:89], v[174:177], v[198:201], v[86:89]
	v_mfma_f32_16x16x32_bf16 v[78:81], v[174:177], v[206:209], v[78:81]
	v_mfma_f32_16x16x32_bf16 v[74:77], v[182:185], v[206:209], v[74:77]
	v_mfma_f32_16x16x32_bf16 v[66:69], v[182:185], v[214:217], v[66:69]
	v_mfma_f32_16x16x32_bf16 v[70:73], v[174:177], v[214:217], v[70:73]
	v_mfma_f32_16x16x32_bf16 v[94:97], v[178:181], v[194:197], v[94:97]
	v_mfma_f32_16x16x32_bf16 v[90:93], v[186:189], v[194:197], v[90:93]
	v_mfma_f32_16x16x32_bf16 v[82:85], v[186:189], v[202:205], v[82:85]
	v_mfma_f32_16x16x32_bf16 v[86:89], v[178:181], v[202:205], v[86:89]
	v_mfma_f32_16x16x32_bf16 v[78:81], v[178:181], v[210:213], v[78:81]
	v_mfma_f32_16x16x32_bf16 v[74:77], v[186:189], v[210:213], v[74:77]
	v_mfma_f32_16x16x32_bf16 v[66:69], v[186:189], v[218:221], v[66:69]
	v_mfma_f32_16x16x32_bf16 v[70:73], v[178:181], v[218:221], v[70:73]
	s_setprio 0
	s_barrier
	s_add_i32 s47, 0, 0x18000
	v_add_u32_e32 v154, s47, v156
	s_add_i32 s48, 0, 0x1c000
	ds_read_b128 v[130:133], v154
	ds_read_b128 v[162:165], v154 offset:1024
	ds_read_b128 v[166:169], v154 offset:2048
	ds_read_b128 v[170:173], v154 offset:3072
	v_add_u32_e32 v154, s48, v156
	ds_read_b128 v[174:177], v154
	ds_read_b128 v[178:181], v154 offset:1024
	ds_read_b128 v[182:185], v154 offset:2048
	ds_read_b128 v[186:189], v154 offset:3072
	s_add_u32 s26, s26, 0x100000
	s_addc_u32 s27, s27, 0
	s_mov_b32 m0, s31
	ds_read_b128 v[190:193], v160 offset:32768
	ds_read_b128 v[194:197], v160 offset:33792
	ds_read_b128 v[198:201], v160 offset:34816
	ds_read_b128 v[202:205], v160 offset:35840
	ds_read_b128 v[206:209], v160 offset:36864
	ds_read_b128 v[210:213], v160 offset:37888
	ds_read_b128 v[214:217], v160 offset:38912
	ds_read_b128 v[218:221], v160 offset:39936
	global_load_lds_dwordx4 v140, s[26:27]
	s_mov_b32 m0, s33
	s_nop 0
	global_load_lds_dwordx4 v136, s[26:27]
	s_waitcnt vmcnt(8)
	s_waitcnt lgkmcnt(0)
	s_barrier
	s_setprio 1
	s_waitcnt lgkmcnt(0)
	v_mfma_f32_16x16x32_bf16 v[62:65], v[130:133], v[190:193], v[62:65]
	v_mfma_f32_16x16x32_bf16 v[58:61], v[166:169], v[190:193], v[58:61]
	v_mfma_f32_16x16x32_bf16 v[50:53], v[166:169], v[198:201], v[50:53]
	v_mfma_f32_16x16x32_bf16 v[54:57], v[130:133], v[198:201], v[54:57]
	v_mfma_f32_16x16x32_bf16 v[46:49], v[130:133], v[206:209], v[46:49]
	v_mfma_f32_16x16x32_bf16 v[42:45], v[166:169], v[206:209], v[42:45]
	v_mfma_f32_16x16x32_bf16 v[34:37], v[166:169], v[214:217], v[34:37]
	v_mfma_f32_16x16x32_bf16 v[38:41], v[130:133], v[214:217], v[38:41]
	v_mfma_f32_16x16x32_bf16 v[62:65], v[162:165], v[194:197], v[62:65]
	v_mfma_f32_16x16x32_bf16 v[58:61], v[170:173], v[194:197], v[58:61]
	v_mfma_f32_16x16x32_bf16 v[50:53], v[170:173], v[202:205], v[50:53]
	v_mfma_f32_16x16x32_bf16 v[54:57], v[162:165], v[202:205], v[54:57]
	v_mfma_f32_16x16x32_bf16 v[46:49], v[162:165], v[210:213], v[46:49]
	v_mfma_f32_16x16x32_bf16 v[42:45], v[170:173], v[210:213], v[42:45]
	v_mfma_f32_16x16x32_bf16 v[34:37], v[170:173], v[218:221], v[34:37]
	v_mfma_f32_16x16x32_bf16 v[38:41], v[162:165], v[218:221], v[38:41]
	s_setprio 0
	s_setprio 1
	v_mfma_f32_16x16x32_bf16 v[126:129], v[174:177], v[190:193], v[126:129]
	v_mfma_f32_16x16x32_bf16 v[122:125], v[182:185], v[190:193], v[122:125]
	v_mfma_f32_16x16x32_bf16 v[114:117], v[182:185], v[198:201], v[114:117]
	v_mfma_f32_16x16x32_bf16 v[118:121], v[174:177], v[198:201], v[118:121]
	v_mfma_f32_16x16x32_bf16 v[110:113], v[174:177], v[206:209], v[110:113]
	v_mfma_f32_16x16x32_bf16 v[106:109], v[182:185], v[206:209], v[106:109]
	v_mfma_f32_16x16x32_bf16 v[98:101], v[182:185], v[214:217], v[98:101]
	v_mfma_f32_16x16x32_bf16 v[102:105], v[174:177], v[214:217], v[102:105]
	v_mfma_f32_16x16x32_bf16 v[126:129], v[178:181], v[194:197], v[126:129]
	v_mfma_f32_16x16x32_bf16 v[122:125], v[186:189], v[194:197], v[122:125]
	v_mfma_f32_16x16x32_bf16 v[114:117], v[186:189], v[202:205], v[114:117]
	v_mfma_f32_16x16x32_bf16 v[118:121], v[178:181], v[202:205], v[118:121]
	v_mfma_f32_16x16x32_bf16 v[110:113], v[178:181], v[210:213], v[110:113]
	v_mfma_f32_16x16x32_bf16 v[106:109], v[186:189], v[210:213], v[106:109]
	v_mfma_f32_16x16x32_bf16 v[98:101], v[186:189], v[218:221], v[98:101]
	v_mfma_f32_16x16x32_bf16 v[102:105], v[178:181], v[218:221], v[102:105]
	s_setprio 0
	s_barrier
	s_add_u32 s26, s24, 0x4000
	s_addc_u32 s27, s25, 0
	s_add_i32 s47, s47, s28
	s_mov_b32 m0, s47
	ds_read_b128 v[190:193], v160 offset:49152
	ds_read_b128 v[194:197], v160 offset:50176
	ds_read_b128 v[198:201], v160 offset:51200
	ds_read_b128 v[202:205], v160 offset:52224
	ds_read_b128 v[206:209], v160 offset:53248
	ds_read_b128 v[210:213], v160 offset:54272
	ds_read_b128 v[214:217], v160 offset:55296
	ds_read_b128 v[218:221], v160 offset:56320
	global_load_lds_dwordx4 v138, s[26:27]
	s_add_i32 m0, s47, 0x2000
	s_add_u32 s24, s24, 0x104000
	s_addc_u32 s25, s25, 0
	global_load_lds_dwordx4 v134, s[26:27]
	s_add_i32 s26, s48, s28
	s_mov_b32 m0, s26
	s_nop 0
	global_load_lds_dwordx4 v138, s[24:25]
	s_add_i32 m0, s26, 0x2000
	s_nop 0
	global_load_lds_dwordx4 v134, s[24:25]
	s_mov_b32 m0, s34
	s_nop 0
	global_load_lds_dwordx4 v140, s[22:23]
	s_mov_b32 m0, s35
	s_nop 0
	global_load_lds_dwordx4 v136, s[22:23]
	s_waitcnt vmcnt(8)
	s_waitcnt lgkmcnt(0)
	s_barrier
	s_setprio 1
	s_waitcnt lgkmcnt(0)
	v_mfma_f32_16x16x32_bf16 v[30:33], v[130:133], v[190:193], v[30:33]
	v_mfma_f32_16x16x32_bf16 v[26:29], v[166:169], v[190:193], v[26:29]
	v_mfma_f32_16x16x32_bf16 v[18:21], v[166:169], v[198:201], v[18:21]
	v_mfma_f32_16x16x32_bf16 v[22:25], v[130:133], v[198:201], v[22:25]
	v_mfma_f32_16x16x32_bf16 v[14:17], v[130:133], v[206:209], v[14:17]
	v_mfma_f32_16x16x32_bf16 v[10:13], v[166:169], v[206:209], v[10:13]
	v_mfma_f32_16x16x32_bf16 v[2:5], v[166:169], v[214:217], v[2:5]
	v_mfma_f32_16x16x32_bf16 v[6:9], v[130:133], v[214:217], v[6:9]
	v_mfma_f32_16x16x32_bf16 v[30:33], v[162:165], v[194:197], v[30:33]
	v_mfma_f32_16x16x32_bf16 v[26:29], v[170:173], v[194:197], v[26:29]
	v_mfma_f32_16x16x32_bf16 v[18:21], v[170:173], v[202:205], v[18:21]
	v_mfma_f32_16x16x32_bf16 v[22:25], v[162:165], v[202:205], v[22:25]
	v_mfma_f32_16x16x32_bf16 v[14:17], v[162:165], v[210:213], v[14:17]
	v_mfma_f32_16x16x32_bf16 v[10:13], v[170:173], v[210:213], v[10:13]
	v_mfma_f32_16x16x32_bf16 v[2:5], v[170:173], v[218:221], v[2:5]
	v_mfma_f32_16x16x32_bf16 v[6:9], v[162:165], v[218:221], v[6:9]
	s_setprio 0
	s_setprio 1
	v_mfma_f32_16x16x32_bf16 v[94:97], v[174:177], v[190:193], v[94:97]
	v_mfma_f32_16x16x32_bf16 v[90:93], v[182:185], v[190:193], v[90:93]
	v_mfma_f32_16x16x32_bf16 v[82:85], v[182:185], v[198:201], v[82:85]
	v_mfma_f32_16x16x32_bf16 v[86:89], v[174:177], v[198:201], v[86:89]
	v_mfma_f32_16x16x32_bf16 v[78:81], v[174:177], v[206:209], v[78:81]
	v_mfma_f32_16x16x32_bf16 v[74:77], v[182:185], v[206:209], v[74:77]
	v_mfma_f32_16x16x32_bf16 v[66:69], v[182:185], v[214:217], v[66:69]
	v_mfma_f32_16x16x32_bf16 v[70:73], v[174:177], v[214:217], v[70:73]
	v_mfma_f32_16x16x32_bf16 v[94:97], v[178:181], v[194:197], v[94:97]
	v_mfma_f32_16x16x32_bf16 v[90:93], v[186:189], v[194:197], v[90:93]
	v_mfma_f32_16x16x32_bf16 v[82:85], v[186:189], v[202:205], v[82:85]
	v_mfma_f32_16x16x32_bf16 v[86:89], v[178:181], v[202:205], v[86:89]
	v_mfma_f32_16x16x32_bf16 v[78:81], v[178:181], v[210:213], v[78:81]
	v_mfma_f32_16x16x32_bf16 v[74:77], v[186:189], v[210:213], v[74:77]
	v_mfma_f32_16x16x32_bf16 v[66:69], v[186:189], v[218:221], v[66:69]
	v_mfma_f32_16x16x32_bf16 v[70:73], v[178:181], v[218:221], v[70:73]
	s_setprio 0
	s_barrier
	s_add_i32 s46, s46, 2
	s_add_u32 s20, s20, 0x8000
	s_addc_u32 s21, s21, 0
	s_add_u32 s44, s44, 0x8000
	s_addc_u32 s45, s45, 0
	s_cmp_gt_u32 s46, 61
	s_cbranch_scc0 .LBB0_109
	s_and_b64 vcc, exec, s[8:9]
	s_cbranch_vccnz .LBB0_113
	v_lshl_add_u32 v154, s4, 8, v1
	s_cmp_lg_u32 s41, 24
	s_mov_b64 s[20:21], -1
	s_cbranch_scc1 .LBB0_114

.LBB0_376:
	ds_read_b128 v[130:133], v159
	ds_read_b128 v[162:165], v159 offset:1024
	ds_read_b128 v[166:169], v159 offset:2048
	ds_read_b128 v[170:173], v159 offset:3072
	ds_read_b128 v[174:177], v160
	ds_read_b128 v[178:181], v160 offset:1024
	ds_read_b128 v[182:185], v160 offset:2048
	ds_read_b128 v[186:189], v160 offset:3072
	s_add_u32 s34, s26, 0xfff04000
	s_addc_u32 s35, s27, -1
	s_cmp_eq_u32 s87, 60
	s_cselect_b32 s38, s80, s34
	s_cselect_b32 s39, s21, s35
	s_cselect_b32 s36, s81, s83
	s_cselect_b32 s37, s19, s86
	s_add_u32 s34, s38, 0x4000
	s_addc_u32 s35, s39, 0
	s_add_i32 m0, s46, 0xc000
	ds_read_b128 v[190:193], v161
	ds_read_b128 v[194:197], v161 offset:1024
	ds_read_b128 v[198:201], v161 offset:2048
	ds_read_b128 v[202:205], v161 offset:3072
	ds_read_b128 v[206:209], v161 offset:4096
	ds_read_b128 v[210:213], v161 offset:5120
	ds_read_b128 v[214:217], v161 offset:6144
	ds_read_b128 v[218:221], v161 offset:7168
	global_load_lds_dwordx4 v146, s[26:27]
	s_add_i32 m0, s46, 0xe000
	s_nop 0
	global_load_lds_dwordx4 v148, s[26:27]
	s_waitcnt vmcnt(8)
	s_waitcnt lgkmcnt(0)
	s_barrier
	s_setprio 1
	s_waitcnt lgkmcnt(0)
	v_mfma_f32_16x16x32_bf16 v[62:65], v[130:133], v[190:193], v[62:65]
	v_mfma_f32_16x16x32_bf16 v[58:61], v[166:169], v[190:193], v[58:61]
	v_mfma_f32_16x16x32_bf16 v[50:53], v[166:169], v[198:201], v[50:53]
	v_mfma_f32_16x16x32_bf16 v[54:57], v[130:133], v[198:201], v[54:57]
	v_mfma_f32_16x16x32_bf16 v[46:49], v[130:133], v[206:209], v[46:49]
	v_mfma_f32_16x16x32_bf16 v[42:45], v[166:169], v[206:209], v[42:45]
	v_mfma_f32_16x16x32_bf16 v[34:37], v[166:169], v[214:217], v[34:37]
	v_mfma_f32_16x16x32_bf16 v[38:41], v[130:133], v[214:217], v[38:41]
	v_mfma_f32_16x16x32_bf16 v[62:65], v[162:165], v[194:197], v[62:65]
	v_mfma_f32_16x16x32_bf16 v[58:61], v[170:173], v[194:197], v[58:61]
	v_mfma_f32_16x16x32_bf16 v[50:53], v[170:173], v[202:205], v[50:53]
	v_mfma_f32_16x16x32_bf16 v[54:57], v[162:165], v[202:205], v[54:57]
	v_mfma_f32_16x16x32_bf16 v[46:49], v[162:165], v[210:213], v[46:49]
	v_mfma_f32_16x16x32_bf16 v[42:45], v[170:173], v[210:213], v[42:45]
	v_mfma_f32_16x16x32_bf16 v[34:37], v[170:173], v[218:221], v[34:37]
	v_mfma_f32_16x16x32_bf16 v[38:41], v[162:165], v[218:221], v[38:41]
	s_setprio 0
	s_setprio 1
	v_mfma_f32_16x16x32_bf16 v[126:129], v[174:177], v[190:193], v[126:129]
	v_mfma_f32_16x16x32_bf16 v[122:125], v[182:185], v[190:193], v[122:125]
	v_mfma_f32_16x16x32_bf16 v[114:117], v[182:185], v[198:201], v[114:117]
	v_mfma_f32_16x16x32_bf16 v[118:121], v[174:177], v[198:201], v[118:121]
	v_mfma_f32_16x16x32_bf16 v[110:113], v[174:177], v[206:209], v[110:113]
	v_mfma_f32_16x16x32_bf16 v[106:109], v[182:185], v[206:209], v[106:109]
	v_mfma_f32_16x16x32_bf16 v[98:101], v[182:185], v[214:217], v[98:101]
	v_mfma_f32_16x16x32_bf16 v[102:105], v[174:177], v[214:217], v[102:105]
	v_mfma_f32_16x16x32_bf16 v[126:129], v[178:181], v[194:197], v[126:129]
	v_mfma_f32_16x16x32_bf16 v[122:125], v[186:189], v[194:197], v[122:125]
	v_mfma_f32_16x16x32_bf16 v[114:117], v[186:189], v[202:205], v[114:117]
	v_mfma_f32_16x16x32_bf16 v[118:121], v[178:181], v[202:205], v[118:121]
	v_mfma_f32_16x16x32_bf16 v[110:113], v[178:181], v[210:213], v[110:113]
	v_mfma_f32_16x16x32_bf16 v[106:109], v[186:189], v[210:213], v[106:109]
	v_mfma_f32_16x16x32_bf16 v[98:101], v[186:189], v[218:221], v[98:101]
	v_mfma_f32_16x16x32_bf16 v[102:105], v[178:181], v[218:221], v[102:105]
	s_setprio 0
	s_barrier
	s_add_i32 s88, s66, s41
	s_mov_b32 m0, s88
	ds_read_b128 v[190:193], v161 offset:16384
	ds_read_b128 v[194:197], v161 offset:17408
	ds_read_b128 v[198:201], v161 offset:18432
	ds_read_b128 v[202:205], v161 offset:19456
	ds_read_b128 v[206:209], v161 offset:20480
	ds_read_b128 v[210:213], v161 offset:21504
	ds_read_b128 v[214:217], v161 offset:22528
	ds_read_b128 v[218:221], v161 offset:23552
	global_load_lds_dwordx4 v138, s[36:37]
	s_add_i32 m0, s88, 0x2000
	s_add_u32 s88, s36, 0x100000
	s_addc_u32 s89, s37, 0
	s_add_i32 vcc_lo, s67, s41
	global_load_lds_dwordx4 v134, s[36:37]
	s_mov_b32 m0, vcc_lo
	s_nop 0
	global_load_lds_dwordx4 v138, s[88:89]
	s_add_i32 m0, vcc_lo, 0x2000
	s_nop 0
	global_load_lds_dwordx4 v134, s[88:89]
	s_mov_b32 m0, s46
	s_nop 0
	global_load_lds_dwordx4 v140, s[38:39]
	s_mov_b32 m0, s47
	s_nop 0
	global_load_lds_dwordx4 v136, s[38:39]
	s_waitcnt vmcnt(8)
	s_waitcnt lgkmcnt(0)
	s_barrier
	s_setprio 1
	s_waitcnt lgkmcnt(0)
	v_mfma_f32_16x16x32_bf16 v[30:33], v[130:133], v[190:193], v[30:33]
	v_mfma_f32_16x16x32_bf16 v[26:29], v[166:169], v[190:193], v[26:29]
	v_mfma_f32_16x16x32_bf16 v[18:21], v[166:169], v[198:201], v[18:21]
	v_mfma_f32_16x16x32_bf16 v[22:25], v[130:133], v[198:201], v[22:25]
	v_mfma_f32_16x16x32_bf16 v[14:17], v[130:133], v[206:209], v[14:17]
	v_mfma_f32_16x16x32_bf16 v[10:13], v[166:169], v[206:209], v[10:13]
	v_mfma_f32_16x16x32_bf16 v[2:5], v[166:169], v[214:217], v[2:5]
	v_mfma_f32_16x16x32_bf16 v[6:9], v[130:133], v[214:217], v[6:9]
	v_mfma_f32_16x16x32_bf16 v[30:33], v[162:165], v[194:197], v[30:33]
	v_mfma_f32_16x16x32_bf16 v[26:29], v[170:173], v[194:197], v[26:29]
	v_mfma_f32_16x16x32_bf16 v[18:21], v[170:173], v[202:205], v[18:21]
	v_mfma_f32_16x16x32_bf16 v[22:25], v[162:165], v[202:205], v[22:25]
	v_mfma_f32_16x16x32_bf16 v[14:17], v[162:165], v[210:213], v[14:17]
	v_mfma_f32_16x16x32_bf16 v[10:13], v[170:173], v[210:213], v[10:13]
	v_mfma_f32_16x16x32_bf16 v[2:5], v[170:173], v[218:221], v[2:5]
	v_mfma_f32_16x16x32_bf16 v[6:9], v[162:165], v[218:221], v[6:9]
	s_setprio 0
	s_setprio 1
	v_mfma_f32_16x16x32_bf16 v[94:97], v[174:177], v[190:193], v[94:97]
	v_mfma_f32_16x16x32_bf16 v[90:93], v[182:185], v[190:193], v[90:93]
	v_mfma_f32_16x16x32_bf16 v[82:85], v[182:185], v[198:201], v[82:85]
	v_mfma_f32_16x16x32_bf16 v[86:89], v[174:177], v[198:201], v[86:89]
	v_mfma_f32_16x16x32_bf16 v[78:81], v[174:177], v[206:209], v[78:81]
	v_mfma_f32_16x16x32_bf16 v[74:77], v[182:185], v[206:209], v[74:77]
	v_mfma_f32_16x16x32_bf16 v[66:69], v[182:185], v[214:217], v[66:69]
	v_mfma_f32_16x16x32_bf16 v[70:73], v[174:177], v[214:217], v[70:73]
	v_mfma_f32_16x16x32_bf16 v[94:97], v[178:181], v[194:197], v[94:97]
	v_mfma_f32_16x16x32_bf16 v[90:93], v[186:189], v[194:197], v[90:93]
	v_mfma_f32_16x16x32_bf16 v[82:85], v[186:189], v[202:205], v[82:85]
	v_mfma_f32_16x16x32_bf16 v[86:89], v[178:181], v[202:205], v[86:89]
	v_mfma_f32_16x16x32_bf16 v[78:81], v[178:181], v[210:213], v[78:81]
	v_mfma_f32_16x16x32_bf16 v[74:77], v[186:189], v[210:213], v[74:77]
	v_mfma_f32_16x16x32_bf16 v[66:69], v[186:189], v[218:221], v[66:69]
	v_mfma_f32_16x16x32_bf16 v[70:73], v[178:181], v[218:221], v[70:73]
	s_setprio 0
	s_barrier
	s_add_i32 s88, 0, 0x18000
	v_add_u32_e32 v154, s88, v157
	s_add_i32 s89, 0, 0x1c000
	ds_read_b128 v[130:133], v154
	ds_read_b128 v[162:165], v154 offset:1024
	ds_read_b128 v[166:169], v154 offset:2048
	ds_read_b128 v[170:173], v154 offset:3072
	v_add_u32_e32 v154, s89, v157
	ds_read_b128 v[174:177], v154
	ds_read_b128 v[178:181], v154 offset:1024
	ds_read_b128 v[182:185], v154 offset:2048
	ds_read_b128 v[186:189], v154 offset:3072
	s_add_u32 s38, s38, 0x100000
	s_addc_u32 s39, s39, 0
	s_mov_b32 m0, s58
	ds_read_b128 v[190:193], v161 offset:32768
	ds_read_b128 v[194:197], v161 offset:33792
	ds_read_b128 v[198:201], v161 offset:34816
	ds_read_b128 v[202:205], v161 offset:35840
	ds_read_b128 v[206:209], v161 offset:36864
	ds_read_b128 v[210:213], v161 offset:37888
	ds_read_b128 v[214:217], v161 offset:38912
	ds_read_b128 v[218:221], v161 offset:39936
	global_load_lds_dwordx4 v140, s[38:39]
	s_mov_b32 m0, s59
	s_nop 0
	global_load_lds_dwordx4 v136, s[38:39]
	s_waitcnt vmcnt(8)
	s_waitcnt lgkmcnt(0)
	s_barrier
	s_setprio 1
	s_waitcnt lgkmcnt(0)
	v_mfma_f32_16x16x32_bf16 v[62:65], v[130:133], v[190:193], v[62:65]
	v_mfma_f32_16x16x32_bf16 v[58:61], v[166:169], v[190:193], v[58:61]
	v_mfma_f32_16x16x32_bf16 v[50:53], v[166:169], v[198:201], v[50:53]
	v_mfma_f32_16x16x32_bf16 v[54:57], v[130:133], v[198:201], v[54:57]
	v_mfma_f32_16x16x32_bf16 v[46:49], v[130:133], v[206:209], v[46:49]
	v_mfma_f32_16x16x32_bf16 v[42:45], v[166:169], v[206:209], v[42:45]
	v_mfma_f32_16x16x32_bf16 v[34:37], v[166:169], v[214:217], v[34:37]
	v_mfma_f32_16x16x32_bf16 v[38:41], v[130:133], v[214:217], v[38:41]
	v_mfma_f32_16x16x32_bf16 v[62:65], v[162:165], v[194:197], v[62:65]
	v_mfma_f32_16x16x32_bf16 v[58:61], v[170:173], v[194:197], v[58:61]
	v_mfma_f32_16x16x32_bf16 v[50:53], v[170:173], v[202:205], v[50:53]
	v_mfma_f32_16x16x32_bf16 v[54:57], v[162:165], v[202:205], v[54:57]
	v_mfma_f32_16x16x32_bf16 v[46:49], v[162:165], v[210:213], v[46:49]
	v_mfma_f32_16x16x32_bf16 v[42:45], v[170:173], v[210:213], v[42:45]
	v_mfma_f32_16x16x32_bf16 v[34:37], v[170:173], v[218:221], v[34:37]
	v_mfma_f32_16x16x32_bf16 v[38:41], v[162:165], v[218:221], v[38:41]
	s_setprio 0
	s_setprio 1
	v_mfma_f32_16x16x32_bf16 v[126:129], v[174:177], v[190:193], v[126:129]
	v_mfma_f32_16x16x32_bf16 v[122:125], v[182:185], v[190:193], v[122:125]
	v_mfma_f32_16x16x32_bf16 v[114:117], v[182:185], v[198:201], v[114:117]
	v_mfma_f32_16x16x32_bf16 v[118:121], v[174:177], v[198:201], v[118:121]
	v_mfma_f32_16x16x32_bf16 v[110:113], v[174:177], v[206:209], v[110:113]
	v_mfma_f32_16x16x32_bf16 v[106:109], v[182:185], v[206:209], v[106:109]
	v_mfma_f32_16x16x32_bf16 v[98:101], v[182:185], v[214:217], v[98:101]
	v_mfma_f32_16x16x32_bf16 v[102:105], v[174:177], v[214:217], v[102:105]
	v_mfma_f32_16x16x32_bf16 v[126:129], v[178:181], v[194:197], v[126:129]
	v_mfma_f32_16x16x32_bf16 v[122:125], v[186:189], v[194:197], v[122:125]
	v_mfma_f32_16x16x32_bf16 v[114:117], v[186:189], v[202:205], v[114:117]
	v_mfma_f32_16x16x32_bf16 v[118:121], v[178:181], v[202:205], v[118:121]
	v_mfma_f32_16x16x32_bf16 v[110:113], v[178:181], v[210:213], v[110:113]
	v_mfma_f32_16x16x32_bf16 v[106:109], v[186:189], v[210:213], v[106:109]
	v_mfma_f32_16x16x32_bf16 v[98:101], v[186:189], v[218:221], v[98:101]
	v_mfma_f32_16x16x32_bf16 v[102:105], v[178:181], v[218:221], v[102:105]
	s_setprio 0
	s_barrier
	s_add_u32 s38, s36, 0x4000
	s_addc_u32 s39, s37, 0
	s_add_i32 s88, s88, s41
	s_mov_b32 m0, s88
	ds_read_b128 v[190:193], v161 offset:49152
	ds_read_b128 v[194:197], v161 offset:50176
	ds_read_b128 v[198:201], v161 offset:51200
	ds_read_b128 v[202:205], v161 offset:52224
	ds_read_b128 v[206:209], v161 offset:53248
	ds_read_b128 v[210:213], v161 offset:54272
	ds_read_b128 v[214:217], v161 offset:55296
	ds_read_b128 v[218:221], v161 offset:56320
	global_load_lds_dwordx4 v138, s[38:39]
	s_add_i32 m0, s88, 0x2000
	s_add_u32 s36, s36, 0x104000
	s_addc_u32 s37, s37, 0
	global_load_lds_dwordx4 v134, s[38:39]
	s_add_i32 s38, s89, s41
	s_mov_b32 m0, s38
	s_nop 0
	global_load_lds_dwordx4 v138, s[36:37]
	s_add_i32 m0, s38, 0x2000
	s_nop 0
	global_load_lds_dwordx4 v134, s[36:37]
	s_mov_b32 m0, s64
	s_nop 0
	global_load_lds_dwordx4 v140, s[34:35]
	s_mov_b32 m0, s65
	s_nop 0
	global_load_lds_dwordx4 v136, s[34:35]
	s_waitcnt vmcnt(8)
	s_waitcnt lgkmcnt(0)
	s_barrier
	s_setprio 1
	s_waitcnt lgkmcnt(0)
	v_mfma_f32_16x16x32_bf16 v[30:33], v[130:133], v[190:193], v[30:33]
	v_mfma_f32_16x16x32_bf16 v[26:29], v[166:169], v[190:193], v[26:29]
	v_mfma_f32_16x16x32_bf16 v[18:21], v[166:169], v[198:201], v[18:21]
	v_mfma_f32_16x16x32_bf16 v[22:25], v[130:133], v[198:201], v[22:25]
	v_mfma_f32_16x16x32_bf16 v[14:17], v[130:133], v[206:209], v[14:17]
	v_mfma_f32_16x16x32_bf16 v[10:13], v[166:169], v[206:209], v[10:13]
	v_mfma_f32_16x16x32_bf16 v[2:5], v[166:169], v[214:217], v[2:5]
	v_mfma_f32_16x16x32_bf16 v[6:9], v[130:133], v[214:217], v[6:9]
	v_mfma_f32_16x16x32_bf16 v[30:33], v[162:165], v[194:197], v[30:33]
	v_mfma_f32_16x16x32_bf16 v[26:29], v[170:173], v[194:197], v[26:29]
	v_mfma_f32_16x16x32_bf16 v[18:21], v[170:173], v[202:205], v[18:21]
	v_mfma_f32_16x16x32_bf16 v[22:25], v[162:165], v[202:205], v[22:25]
	v_mfma_f32_16x16x32_bf16 v[14:17], v[162:165], v[210:213], v[14:17]
	v_mfma_f32_16x16x32_bf16 v[10:13], v[170:173], v[210:213], v[10:13]
	v_mfma_f32_16x16x32_bf16 v[2:5], v[170:173], v[218:221], v[2:5]
	v_mfma_f32_16x16x32_bf16 v[6:9], v[162:165], v[218:221], v[6:9]
	s_setprio 0
	s_setprio 1
	v_mfma_f32_16x16x32_bf16 v[94:97], v[174:177], v[190:193], v[94:97]
	v_mfma_f32_16x16x32_bf16 v[90:93], v[182:185], v[190:193], v[90:93]
	v_mfma_f32_16x16x32_bf16 v[82:85], v[182:185], v[198:201], v[82:85]
	v_mfma_f32_16x16x32_bf16 v[86:89], v[174:177], v[198:201], v[86:89]
	v_mfma_f32_16x16x32_bf16 v[78:81], v[174:177], v[206:209], v[78:81]
	v_mfma_f32_16x16x32_bf16 v[74:77], v[182:185], v[206:209], v[74:77]
	v_mfma_f32_16x16x32_bf16 v[66:69], v[182:185], v[214:217], v[66:69]
	v_mfma_f32_16x16x32_bf16 v[70:73], v[174:177], v[214:217], v[70:73]
	v_mfma_f32_16x16x32_bf16 v[94:97], v[178:181], v[194:197], v[94:97]
	v_mfma_f32_16x16x32_bf16 v[90:93], v[186:189], v[194:197], v[90:93]
	v_mfma_f32_16x16x32_bf16 v[82:85], v[186:189], v[202:205], v[82:85]
	v_mfma_f32_16x16x32_bf16 v[86:89], v[178:181], v[202:205], v[86:89]
	v_mfma_f32_16x16x32_bf16 v[78:81], v[178:181], v[210:213], v[78:81]
	v_mfma_f32_16x16x32_bf16 v[74:77], v[186:189], v[210:213], v[74:77]
	v_mfma_f32_16x16x32_bf16 v[66:69], v[186:189], v[218:221], v[66:69]
	v_mfma_f32_16x16x32_bf16 v[70:73], v[178:181], v[218:221], v[70:73]
	s_setprio 0
	s_barrier
	s_add_i32 s87, s87, 2
	s_add_u32 s26, s26, 0x8000
	s_addc_u32 s27, s27, 0
	s_add_u32 s83, s83, 0x8000
	s_addc_u32 s86, s86, 0
	s_cmp_gt_u32 s87, 61
	s_cbranch_scc0 .LBB0_376
	s_and_b64 vcc, exec, s[14:15]
	s_cbranch_vccz .LBB0_379
	s_barrier

.LBB0_536:
	ds_read_b128 v[130:133], v159
	ds_read_b128 v[162:165], v159 offset:1024
	ds_read_b128 v[166:169], v159 offset:2048
	ds_read_b128 v[170:173], v159 offset:3072
	ds_read_b128 v[174:177], v160
	ds_read_b128 v[178:181], v160 offset:1024
	ds_read_b128 v[182:185], v160 offset:2048
	ds_read_b128 v[186:189], v160 offset:3072
	s_add_u32 s30, s26, 0xfff04000
	s_addc_u32 s31, s27, -1
	s_cmp_eq_u32 s80, 60
	s_cselect_b32 s36, s74, s30
	s_cselect_b32 s37, s21, s31
	s_cselect_b32 s34, s75, s78
	s_cselect_b32 s35, s19, s79
	s_add_u32 s30, s36, 0x4000
	s_addc_u32 s31, s37, 0
	s_add_i32 m0, s42, 0xc000
	ds_read_b128 v[190:193], v161
	ds_read_b128 v[194:197], v161 offset:1024
	ds_read_b128 v[198:201], v161 offset:2048
	ds_read_b128 v[202:205], v161 offset:3072
	ds_read_b128 v[206:209], v161 offset:4096
	ds_read_b128 v[210:213], v161 offset:5120
	ds_read_b128 v[214:217], v161 offset:6144
	ds_read_b128 v[218:221], v161 offset:7168
	global_load_lds_dwordx4 v146, s[26:27]
	s_add_i32 m0, s42, 0xe000
	s_nop 0
	global_load_lds_dwordx4 v148, s[26:27]
	s_waitcnt vmcnt(8)
	s_waitcnt lgkmcnt(0)
	s_barrier
	s_setprio 1
	s_waitcnt lgkmcnt(0)
	v_mfma_f32_16x16x32_bf16 v[62:65], v[130:133], v[190:193], v[62:65]
	v_mfma_f32_16x16x32_bf16 v[58:61], v[166:169], v[190:193], v[58:61]
	v_mfma_f32_16x16x32_bf16 v[50:53], v[166:169], v[198:201], v[50:53]
	v_mfma_f32_16x16x32_bf16 v[54:57], v[130:133], v[198:201], v[54:57]
	v_mfma_f32_16x16x32_bf16 v[46:49], v[130:133], v[206:209], v[46:49]
	v_mfma_f32_16x16x32_bf16 v[42:45], v[166:169], v[206:209], v[42:45]
	v_mfma_f32_16x16x32_bf16 v[34:37], v[166:169], v[214:217], v[34:37]
	v_mfma_f32_16x16x32_bf16 v[38:41], v[130:133], v[214:217], v[38:41]
	v_mfma_f32_16x16x32_bf16 v[62:65], v[162:165], v[194:197], v[62:65]
	v_mfma_f32_16x16x32_bf16 v[58:61], v[170:173], v[194:197], v[58:61]
	v_mfma_f32_16x16x32_bf16 v[50:53], v[170:173], v[202:205], v[50:53]
	v_mfma_f32_16x16x32_bf16 v[54:57], v[162:165], v[202:205], v[54:57]
	v_mfma_f32_16x16x32_bf16 v[46:49], v[162:165], v[210:213], v[46:49]
	v_mfma_f32_16x16x32_bf16 v[42:45], v[170:173], v[210:213], v[42:45]
	v_mfma_f32_16x16x32_bf16 v[34:37], v[170:173], v[218:221], v[34:37]
	v_mfma_f32_16x16x32_bf16 v[38:41], v[162:165], v[218:221], v[38:41]
	s_setprio 0
	s_setprio 1
	v_mfma_f32_16x16x32_bf16 v[126:129], v[174:177], v[190:193], v[126:129]
	v_mfma_f32_16x16x32_bf16 v[122:125], v[182:185], v[190:193], v[122:125]
	v_mfma_f32_16x16x32_bf16 v[114:117], v[182:185], v[198:201], v[114:117]
	v_mfma_f32_16x16x32_bf16 v[118:121], v[174:177], v[198:201], v[118:121]
	v_mfma_f32_16x16x32_bf16 v[110:113], v[174:177], v[206:209], v[110:113]
	v_mfma_f32_16x16x32_bf16 v[106:109], v[182:185], v[206:209], v[106:109]
	v_mfma_f32_16x16x32_bf16 v[98:101], v[182:185], v[214:217], v[98:101]
	v_mfma_f32_16x16x32_bf16 v[102:105], v[174:177], v[214:217], v[102:105]
	v_mfma_f32_16x16x32_bf16 v[126:129], v[178:181], v[194:197], v[126:129]
	v_mfma_f32_16x16x32_bf16 v[122:125], v[186:189], v[194:197], v[122:125]
	v_mfma_f32_16x16x32_bf16 v[114:117], v[186:189], v[202:205], v[114:117]
	v_mfma_f32_16x16x32_bf16 v[118:121], v[178:181], v[202:205], v[118:121]
	v_mfma_f32_16x16x32_bf16 v[110:113], v[178:181], v[210:213], v[110:113]
	v_mfma_f32_16x16x32_bf16 v[106:109], v[186:189], v[210:213], v[106:109]
	v_mfma_f32_16x16x32_bf16 v[98:101], v[186:189], v[218:221], v[98:101]
	v_mfma_f32_16x16x32_bf16 v[102:105], v[178:181], v[218:221], v[102:105]
	s_setprio 0
	s_barrier
	s_add_i32 s81, s62, s38
	s_mov_b32 m0, s81
	ds_read_b128 v[190:193], v161 offset:16384
	ds_read_b128 v[194:197], v161 offset:17408
	ds_read_b128 v[198:201], v161 offset:18432
	ds_read_b128 v[202:205], v161 offset:19456
	ds_read_b128 v[206:209], v161 offset:20480
	ds_read_b128 v[210:213], v161 offset:21504
	ds_read_b128 v[214:217], v161 offset:22528
	ds_read_b128 v[218:221], v161 offset:23552
	global_load_lds_dwordx4 v138, s[34:35]
	s_add_i32 m0, s81, 0x2000
	s_add_u32 s86, s34, 0x100000
	s_addc_u32 s87, s35, 0
	s_add_i32 s81, s63, s38
	global_load_lds_dwordx4 v134, s[34:35]
	s_mov_b32 m0, s81
	s_nop 0
	global_load_lds_dwordx4 v138, s[86:87]
	s_add_i32 m0, s81, 0x2000
	s_nop 0
	global_load_lds_dwordx4 v134, s[86:87]
	s_mov_b32 m0, s42
	s_nop 0
	global_load_lds_dwordx4 v140, s[36:37]
	s_mov_b32 m0, s43
	s_nop 0
	global_load_lds_dwordx4 v136, s[36:37]
	s_waitcnt vmcnt(8)
	s_waitcnt lgkmcnt(0)
	s_barrier
	s_setprio 1
	s_waitcnt lgkmcnt(0)
	v_mfma_f32_16x16x32_bf16 v[30:33], v[130:133], v[190:193], v[30:33]
	v_mfma_f32_16x16x32_bf16 v[26:29], v[166:169], v[190:193], v[26:29]
	v_mfma_f32_16x16x32_bf16 v[18:21], v[166:169], v[198:201], v[18:21]
	v_mfma_f32_16x16x32_bf16 v[22:25], v[130:133], v[198:201], v[22:25]
	v_mfma_f32_16x16x32_bf16 v[14:17], v[130:133], v[206:209], v[14:17]
	v_mfma_f32_16x16x32_bf16 v[10:13], v[166:169], v[206:209], v[10:13]
	v_mfma_f32_16x16x32_bf16 v[2:5], v[166:169], v[214:217], v[2:5]
	v_mfma_f32_16x16x32_bf16 v[6:9], v[130:133], v[214:217], v[6:9]
	v_mfma_f32_16x16x32_bf16 v[30:33], v[162:165], v[194:197], v[30:33]
	v_mfma_f32_16x16x32_bf16 v[26:29], v[170:173], v[194:197], v[26:29]
	v_mfma_f32_16x16x32_bf16 v[18:21], v[170:173], v[202:205], v[18:21]
	v_mfma_f32_16x16x32_bf16 v[22:25], v[162:165], v[202:205], v[22:25]
	v_mfma_f32_16x16x32_bf16 v[14:17], v[162:165], v[210:213], v[14:17]
	v_mfma_f32_16x16x32_bf16 v[10:13], v[170:173], v[210:213], v[10:13]
	v_mfma_f32_16x16x32_bf16 v[2:5], v[170:173], v[218:221], v[2:5]
	v_mfma_f32_16x16x32_bf16 v[6:9], v[162:165], v[218:221], v[6:9]
	s_setprio 0
	s_setprio 1
	v_mfma_f32_16x16x32_bf16 v[94:97], v[174:177], v[190:193], v[94:97]
	v_mfma_f32_16x16x32_bf16 v[90:93], v[182:185], v[190:193], v[90:93]
	v_mfma_f32_16x16x32_bf16 v[82:85], v[182:185], v[198:201], v[82:85]
	v_mfma_f32_16x16x32_bf16 v[86:89], v[174:177], v[198:201], v[86:89]
	v_mfma_f32_16x16x32_bf16 v[78:81], v[174:177], v[206:209], v[78:81]
	v_mfma_f32_16x16x32_bf16 v[74:77], v[182:185], v[206:209], v[74:77]
	v_mfma_f32_16x16x32_bf16 v[66:69], v[182:185], v[214:217], v[66:69]
	v_mfma_f32_16x16x32_bf16 v[70:73], v[174:177], v[214:217], v[70:73]
	v_mfma_f32_16x16x32_bf16 v[94:97], v[178:181], v[194:197], v[94:97]
	v_mfma_f32_16x16x32_bf16 v[90:93], v[186:189], v[194:197], v[90:93]
	v_mfma_f32_16x16x32_bf16 v[82:85], v[186:189], v[202:205], v[82:85]
	v_mfma_f32_16x16x32_bf16 v[86:89], v[178:181], v[202:205], v[86:89]
	v_mfma_f32_16x16x32_bf16 v[78:81], v[178:181], v[210:213], v[78:81]
	v_mfma_f32_16x16x32_bf16 v[74:77], v[186:189], v[210:213], v[74:77]
	v_mfma_f32_16x16x32_bf16 v[66:69], v[186:189], v[218:221], v[66:69]
	v_mfma_f32_16x16x32_bf16 v[70:73], v[178:181], v[218:221], v[70:73]
	s_setprio 0
	s_barrier
	s_add_i32 s81, 0, 0x18000
	v_add_u32_e32 v154, s81, v157
	s_add_i32 s83, 0, 0x1c000
	ds_read_b128 v[130:133], v154
	ds_read_b128 v[162:165], v154 offset:1024
	ds_read_b128 v[166:169], v154 offset:2048
	ds_read_b128 v[170:173], v154 offset:3072
	v_add_u32_e32 v154, s83, v157
	ds_read_b128 v[174:177], v154
	ds_read_b128 v[178:181], v154 offset:1024
	ds_read_b128 v[182:185], v154 offset:2048
	ds_read_b128 v[186:189], v154 offset:3072
	s_add_u32 s36, s36, 0x100000
	s_addc_u32 s37, s37, 0
	s_mov_b32 m0, s46
	ds_read_b128 v[190:193], v161 offset:32768
	ds_read_b128 v[194:197], v161 offset:33792
	ds_read_b128 v[198:201], v161 offset:34816
	ds_read_b128 v[202:205], v161 offset:35840
	ds_read_b128 v[206:209], v161 offset:36864
	ds_read_b128 v[210:213], v161 offset:37888
	ds_read_b128 v[214:217], v161 offset:38912
	ds_read_b128 v[218:221], v161 offset:39936
	global_load_lds_dwordx4 v140, s[36:37]
	s_mov_b32 m0, s47
	s_nop 0
	global_load_lds_dwordx4 v136, s[36:37]
	s_waitcnt vmcnt(8)
	s_waitcnt lgkmcnt(0)
	s_barrier
	s_setprio 1
	s_waitcnt lgkmcnt(0)
	v_mfma_f32_16x16x32_bf16 v[62:65], v[130:133], v[190:193], v[62:65]
	v_mfma_f32_16x16x32_bf16 v[58:61], v[166:169], v[190:193], v[58:61]
	v_mfma_f32_16x16x32_bf16 v[50:53], v[166:169], v[198:201], v[50:53]
	v_mfma_f32_16x16x32_bf16 v[54:57], v[130:133], v[198:201], v[54:57]
	v_mfma_f32_16x16x32_bf16 v[46:49], v[130:133], v[206:209], v[46:49]
	v_mfma_f32_16x16x32_bf16 v[42:45], v[166:169], v[206:209], v[42:45]
	v_mfma_f32_16x16x32_bf16 v[34:37], v[166:169], v[214:217], v[34:37]
	v_mfma_f32_16x16x32_bf16 v[38:41], v[130:133], v[214:217], v[38:41]
	v_mfma_f32_16x16x32_bf16 v[62:65], v[162:165], v[194:197], v[62:65]
	v_mfma_f32_16x16x32_bf16 v[58:61], v[170:173], v[194:197], v[58:61]
	v_mfma_f32_16x16x32_bf16 v[50:53], v[170:173], v[202:205], v[50:53]
	v_mfma_f32_16x16x32_bf16 v[54:57], v[162:165], v[202:205], v[54:57]
	v_mfma_f32_16x16x32_bf16 v[46:49], v[162:165], v[210:213], v[46:49]
	v_mfma_f32_16x16x32_bf16 v[42:45], v[170:173], v[210:213], v[42:45]
	v_mfma_f32_16x16x32_bf16 v[34:37], v[170:173], v[218:221], v[34:37]
	v_mfma_f32_16x16x32_bf16 v[38:41], v[162:165], v[218:221], v[38:41]
	s_setprio 0
	s_setprio 1
	v_mfma_f32_16x16x32_bf16 v[126:129], v[174:177], v[190:193], v[126:129]
	v_mfma_f32_16x16x32_bf16 v[122:125], v[182:185], v[190:193], v[122:125]
	v_mfma_f32_16x16x32_bf16 v[114:117], v[182:185], v[198:201], v[114:117]
	v_mfma_f32_16x16x32_bf16 v[118:121], v[174:177], v[198:201], v[118:121]
	v_mfma_f32_16x16x32_bf16 v[110:113], v[174:177], v[206:209], v[110:113]
	v_mfma_f32_16x16x32_bf16 v[106:109], v[182:185], v[206:209], v[106:109]
	v_mfma_f32_16x16x32_bf16 v[98:101], v[182:185], v[214:217], v[98:101]
	v_mfma_f32_16x16x32_bf16 v[102:105], v[174:177], v[214:217], v[102:105]
	v_mfma_f32_16x16x32_bf16 v[126:129], v[178:181], v[194:197], v[126:129]
	v_mfma_f32_16x16x32_bf16 v[122:125], v[186:189], v[194:197], v[122:125]
	v_mfma_f32_16x16x32_bf16 v[114:117], v[186:189], v[202:205], v[114:117]
	v_mfma_f32_16x16x32_bf16 v[118:121], v[178:181], v[202:205], v[118:121]
	v_mfma_f32_16x16x32_bf16 v[110:113], v[178:181], v[210:213], v[110:113]
	v_mfma_f32_16x16x32_bf16 v[106:109], v[186:189], v[210:213], v[106:109]
	v_mfma_f32_16x16x32_bf16 v[98:101], v[186:189], v[218:221], v[98:101]
	v_mfma_f32_16x16x32_bf16 v[102:105], v[178:181], v[218:221], v[102:105]
	s_setprio 0
	s_barrier
	s_add_u32 s36, s34, 0x4000
	s_addc_u32 s37, s35, 0
	s_add_i32 s81, s81, s38
	s_mov_b32 m0, s81
	ds_read_b128 v[190:193], v161 offset:49152
	ds_read_b128 v[194:197], v161 offset:50176
	ds_read_b128 v[198:201], v161 offset:51200
	ds_read_b128 v[202:205], v161 offset:52224
	ds_read_b128 v[206:209], v161 offset:53248
	ds_read_b128 v[210:213], v161 offset:54272
	ds_read_b128 v[214:217], v161 offset:55296
	ds_read_b128 v[218:221], v161 offset:56320
	global_load_lds_dwordx4 v138, s[36:37]
	s_add_i32 m0, s81, 0x2000
	s_add_u32 s34, s34, 0x104000
	s_addc_u32 s35, s35, 0
	global_load_lds_dwordx4 v134, s[36:37]
	s_add_i32 s36, s83, s38
	s_mov_b32 m0, s36
	s_nop 0
	global_load_lds_dwordx4 v138, s[34:35]
	s_add_i32 m0, s36, 0x2000
	s_nop 0
	global_load_lds_dwordx4 v134, s[34:35]
	s_mov_b32 m0, s58
	s_nop 0
	global_load_lds_dwordx4 v140, s[30:31]
	s_mov_b32 m0, s59
	s_nop 0
	global_load_lds_dwordx4 v136, s[30:31]
	s_waitcnt vmcnt(8)
	s_waitcnt lgkmcnt(0)
	s_barrier
	s_setprio 1
	s_waitcnt lgkmcnt(0)
	v_mfma_f32_16x16x32_bf16 v[30:33], v[130:133], v[190:193], v[30:33]
	v_mfma_f32_16x16x32_bf16 v[26:29], v[166:169], v[190:193], v[26:29]
	v_mfma_f32_16x16x32_bf16 v[18:21], v[166:169], v[198:201], v[18:21]
	v_mfma_f32_16x16x32_bf16 v[22:25], v[130:133], v[198:201], v[22:25]
	v_mfma_f32_16x16x32_bf16 v[14:17], v[130:133], v[206:209], v[14:17]
	v_mfma_f32_16x16x32_bf16 v[10:13], v[166:169], v[206:209], v[10:13]
	v_mfma_f32_16x16x32_bf16 v[2:5], v[166:169], v[214:217], v[2:5]
	v_mfma_f32_16x16x32_bf16 v[6:9], v[130:133], v[214:217], v[6:9]
	v_mfma_f32_16x16x32_bf16 v[30:33], v[162:165], v[194:197], v[30:33]
	v_mfma_f32_16x16x32_bf16 v[26:29], v[170:173], v[194:197], v[26:29]
	v_mfma_f32_16x16x32_bf16 v[18:21], v[170:173], v[202:205], v[18:21]
	v_mfma_f32_16x16x32_bf16 v[22:25], v[162:165], v[202:205], v[22:25]
	v_mfma_f32_16x16x32_bf16 v[14:17], v[162:165], v[210:213], v[14:17]
	v_mfma_f32_16x16x32_bf16 v[10:13], v[170:173], v[210:213], v[10:13]
	v_mfma_f32_16x16x32_bf16 v[2:5], v[170:173], v[218:221], v[2:5]
	v_mfma_f32_16x16x32_bf16 v[6:9], v[162:165], v[218:221], v[6:9]
	s_setprio 0
	s_setprio 1
	v_mfma_f32_16x16x32_bf16 v[94:97], v[174:177], v[190:193], v[94:97]
	v_mfma_f32_16x16x32_bf16 v[90:93], v[182:185], v[190:193], v[90:93]
	v_mfma_f32_16x16x32_bf16 v[82:85], v[182:185], v[198:201], v[82:85]
	v_mfma_f32_16x16x32_bf16 v[86:89], v[174:177], v[198:201], v[86:89]
	v_mfma_f32_16x16x32_bf16 v[78:81], v[174:177], v[206:209], v[78:81]
	v_mfma_f32_16x16x32_bf16 v[74:77], v[182:185], v[206:209], v[74:77]
	v_mfma_f32_16x16x32_bf16 v[66:69], v[182:185], v[214:217], v[66:69]
	v_mfma_f32_16x16x32_bf16 v[70:73], v[174:177], v[214:217], v[70:73]
	v_mfma_f32_16x16x32_bf16 v[94:97], v[178:181], v[194:197], v[94:97]
	v_mfma_f32_16x16x32_bf16 v[90:93], v[186:189], v[194:197], v[90:93]
	v_mfma_f32_16x16x32_bf16 v[82:85], v[186:189], v[202:205], v[82:85]
	v_mfma_f32_16x16x32_bf16 v[86:89], v[178:181], v[202:205], v[86:89]
	v_mfma_f32_16x16x32_bf16 v[78:81], v[178:181], v[210:213], v[78:81]
	v_mfma_f32_16x16x32_bf16 v[74:77], v[186:189], v[210:213], v[74:77]
	v_mfma_f32_16x16x32_bf16 v[66:69], v[186:189], v[218:221], v[66:69]
	v_mfma_f32_16x16x32_bf16 v[70:73], v[178:181], v[218:221], v[70:73]
	s_setprio 0
	s_barrier
	s_add_i32 s80, s80, 2
	s_add_u32 s26, s26, 0x8000
	s_addc_u32 s27, s27, 0
	s_add_u32 s78, s78, 0x8000
	s_addc_u32 s79, s79, 0
	s_cmp_gt_u32 s80, 61
	s_cbranch_scc0 .LBB0_536
	s_and_b64 vcc, exec, s[14:15]
	s_cbranch_vccz .LBB0_539
	s_barrier

.LBB0_1005:
	v_add_u32_e32 v142, s46, v200
	v_add_u32_e32 v158, s47, v200
	ds_read_b128 v[130:133], v142
	ds_read_b128 v[134:137], v142 offset:1024
	ds_read_b128 v[138:141], v142 offset:2048
	ds_read_b128 v[142:145], v142 offset:3072
	ds_read_b128 v[146:149], v158
	ds_read_b128 v[150:153], v158 offset:1024
	ds_read_b128 v[154:157], v158 offset:2048
	ds_read_b128 v[158:161], v158 offset:3072
	s_add_i32 s70, s31, 2
	s_add_u32 s26, s24, 0xfff44000
	s_addc_u32 s27, s25, -1
	s_cmp_eq_u32 s67, s31
	s_cselect_b32 s34, s6, s26
	s_cselect_b32 s35, s7, s27
	s_cselect_b32 s30, s20, s68
	s_cselect_b32 s31, s21, s69
	s_add_u32 s26, s34, 0x4000
	s_addc_u32 s27, s35, 0
	s_add_i32 m0, s37, 0xc000
	ds_read_b128 v[162:165], v201
	ds_read_b128 v[166:169], v201 offset:1024
	ds_read_b128 v[170:173], v201 offset:2048
	ds_read_b128 v[174:177], v201 offset:3072
	ds_read_b128 v[202:205], v201 offset:4096
	ds_read_b128 v[206:209], v201 offset:5120
	ds_read_b128 v[210:213], v201 offset:6144
	ds_read_b128 v[214:217], v201 offset:7168
	global_load_lds_dwordx4 v190, s[24:25]
	s_add_i32 m0, s37, 0xe000
	s_nop 0
	global_load_lds_dwordx4 v192, s[24:25]
	s_waitcnt vmcnt(8)
	s_waitcnt lgkmcnt(0)
	s_barrier
	s_setprio 1
	s_waitcnt lgkmcnt(0)
	v_mfma_f32_16x16x32_bf16 v[126:129], v[130:133], v[162:165], v[126:129]
	v_mfma_f32_16x16x32_bf16 v[122:125], v[138:141], v[162:165], v[122:125]
	v_mfma_f32_16x16x32_bf16 v[114:117], v[138:141], v[170:173], v[114:117]
	v_mfma_f32_16x16x32_bf16 v[118:121], v[130:133], v[170:173], v[118:121]
	v_mfma_f32_16x16x32_bf16 v[110:113], v[130:133], v[202:205], v[110:113]
	v_mfma_f32_16x16x32_bf16 v[106:109], v[138:141], v[202:205], v[106:109]
	v_mfma_f32_16x16x32_bf16 v[98:101], v[138:141], v[210:213], v[98:101]
	v_mfma_f32_16x16x32_bf16 v[102:105], v[130:133], v[210:213], v[102:105]
	v_mfma_f32_16x16x32_bf16 v[126:129], v[134:137], v[166:169], v[126:129]
	v_mfma_f32_16x16x32_bf16 v[122:125], v[142:145], v[166:169], v[122:125]
	v_mfma_f32_16x16x32_bf16 v[114:117], v[142:145], v[174:177], v[114:117]
	v_mfma_f32_16x16x32_bf16 v[118:121], v[134:137], v[174:177], v[118:121]
	v_mfma_f32_16x16x32_bf16 v[110:113], v[134:137], v[206:209], v[110:113]
	v_mfma_f32_16x16x32_bf16 v[106:109], v[142:145], v[206:209], v[106:109]
	v_mfma_f32_16x16x32_bf16 v[98:101], v[142:145], v[214:217], v[98:101]
	v_mfma_f32_16x16x32_bf16 v[102:105], v[134:137], v[214:217], v[102:105]
	s_setprio 0
	s_setprio 1
	v_mfma_f32_16x16x32_bf16 v[94:97], v[146:149], v[162:165], v[94:97]
	v_mfma_f32_16x16x32_bf16 v[90:93], v[154:157], v[162:165], v[90:93]
	v_mfma_f32_16x16x32_bf16 v[82:85], v[154:157], v[170:173], v[82:85]
	v_mfma_f32_16x16x32_bf16 v[86:89], v[146:149], v[170:173], v[86:89]
	v_mfma_f32_16x16x32_bf16 v[78:81], v[146:149], v[202:205], v[78:81]
	v_mfma_f32_16x16x32_bf16 v[74:77], v[154:157], v[202:205], v[74:77]
	v_mfma_f32_16x16x32_bf16 v[58:61], v[154:157], v[210:213], v[58:61]
	v_mfma_f32_16x16x32_bf16 v[66:69], v[146:149], v[210:213], v[66:69]
	v_mfma_f32_16x16x32_bf16 v[94:97], v[150:153], v[166:169], v[94:97]
	v_mfma_f32_16x16x32_bf16 v[90:93], v[158:161], v[166:169], v[90:93]
	v_mfma_f32_16x16x32_bf16 v[82:85], v[158:161], v[174:177], v[82:85]
	v_mfma_f32_16x16x32_bf16 v[86:89], v[150:153], v[174:177], v[86:89]
	v_mfma_f32_16x16x32_bf16 v[78:81], v[150:153], v[206:209], v[78:81]
	v_mfma_f32_16x16x32_bf16 v[74:77], v[158:161], v[206:209], v[74:77]
	v_mfma_f32_16x16x32_bf16 v[58:61], v[158:161], v[214:217], v[58:61]
	v_mfma_f32_16x16x32_bf16 v[66:69], v[150:153], v[214:217], v[66:69]
	s_setprio 0
	s_barrier
	s_add_i32 s71, s46, s36
	s_mov_b32 m0, s71
	ds_read_b128 v[162:165], v201 offset:16384
	ds_read_b128 v[166:169], v201 offset:17408
	ds_read_b128 v[170:173], v201 offset:18432
	ds_read_b128 v[174:177], v201 offset:19456
	ds_read_b128 v[202:205], v201 offset:20480
	ds_read_b128 v[206:209], v201 offset:21504
	ds_read_b128 v[210:213], v201 offset:22528
	ds_read_b128 v[214:217], v201 offset:23552
	global_load_lds_dwordx4 v182, s[30:31]
	s_add_i32 m0, s71, 0x2000
	s_add_u32 s72, s30, 0xc0000
	s_addc_u32 s73, s31, 0
	s_add_i32 s71, s47, s36
	global_load_lds_dwordx4 v178, s[30:31]
	s_mov_b32 m0, s71
	s_nop 0
	global_load_lds_dwordx4 v182, s[72:73]
	s_add_i32 m0, s71, 0x2000
	s_nop 0
	global_load_lds_dwordx4 v178, s[72:73]
	s_mov_b32 m0, s37
	s_nop 0
	global_load_lds_dwordx4 v184, s[34:35]
	s_mov_b32 m0, s38
	s_nop 0
	global_load_lds_dwordx4 v180, s[34:35]
	s_waitcnt vmcnt(8)
	s_waitcnt lgkmcnt(0)
	s_barrier
	s_setprio 1
	s_waitcnt lgkmcnt(0)
	v_mfma_f32_16x16x32_bf16 v[70:73], v[130:133], v[162:165], v[70:73]
	v_mfma_f32_16x16x32_bf16 v[62:65], v[138:141], v[162:165], v[62:65]
	v_mfma_f32_16x16x32_bf16 v[50:53], v[138:141], v[170:173], v[50:53]
	v_mfma_f32_16x16x32_bf16 v[54:57], v[130:133], v[170:173], v[54:57]
	v_mfma_f32_16x16x32_bf16 v[46:49], v[130:133], v[202:205], v[46:49]
	v_mfma_f32_16x16x32_bf16 v[42:45], v[138:141], v[202:205], v[42:45]
	v_mfma_f32_16x16x32_bf16 v[34:37], v[138:141], v[210:213], v[34:37]
	v_mfma_f32_16x16x32_bf16 v[38:41], v[130:133], v[210:213], v[38:41]
	v_mfma_f32_16x16x32_bf16 v[70:73], v[134:137], v[166:169], v[70:73]
	v_mfma_f32_16x16x32_bf16 v[62:65], v[142:145], v[166:169], v[62:65]
	v_mfma_f32_16x16x32_bf16 v[50:53], v[142:145], v[174:177], v[50:53]
	v_mfma_f32_16x16x32_bf16 v[54:57], v[134:137], v[174:177], v[54:57]
	v_mfma_f32_16x16x32_bf16 v[46:49], v[134:137], v[206:209], v[46:49]
	v_mfma_f32_16x16x32_bf16 v[42:45], v[142:145], v[206:209], v[42:45]
	v_mfma_f32_16x16x32_bf16 v[34:37], v[142:145], v[214:217], v[34:37]
	v_mfma_f32_16x16x32_bf16 v[38:41], v[134:137], v[214:217], v[38:41]
	s_setprio 0
	s_setprio 1
	v_mfma_f32_16x16x32_bf16 v[30:33], v[146:149], v[162:165], v[30:33]
	v_mfma_f32_16x16x32_bf16 v[26:29], v[154:157], v[162:165], v[26:29]
	v_mfma_f32_16x16x32_bf16 v[18:21], v[154:157], v[170:173], v[18:21]
	v_mfma_f32_16x16x32_bf16 v[22:25], v[146:149], v[170:173], v[22:25]
	v_mfma_f32_16x16x32_bf16 v[14:17], v[146:149], v[202:205], v[14:17]
	v_mfma_f32_16x16x32_bf16 v[10:13], v[154:157], v[202:205], v[10:13]
	v_mfma_f32_16x16x32_bf16 v[2:5], v[154:157], v[210:213], v[2:5]
	v_mfma_f32_16x16x32_bf16 v[6:9], v[146:149], v[210:213], v[6:9]
	v_mfma_f32_16x16x32_bf16 v[30:33], v[150:153], v[166:169], v[30:33]
	v_mfma_f32_16x16x32_bf16 v[26:29], v[158:161], v[166:169], v[26:29]
	v_mfma_f32_16x16x32_bf16 v[18:21], v[158:161], v[174:177], v[18:21]
	v_mfma_f32_16x16x32_bf16 v[22:25], v[150:153], v[174:177], v[22:25]
	v_mfma_f32_16x16x32_bf16 v[14:17], v[150:153], v[206:209], v[14:17]
	v_mfma_f32_16x16x32_bf16 v[10:13], v[158:161], v[206:209], v[10:13]
	v_mfma_f32_16x16x32_bf16 v[2:5], v[158:161], v[214:217], v[2:5]
	v_mfma_f32_16x16x32_bf16 v[6:9], v[150:153], v[214:217], v[6:9]
	s_setprio 0
	s_barrier
	s_add_i32 s71, 0, 0x18000
	s_add_i32 s72, 0, 0x1c000
	v_add_u32_e32 v142, s71, v200
	v_add_u32_e32 v158, s72, v200
	ds_read_b128 v[130:133], v142
	ds_read_b128 v[134:137], v142 offset:1024
	ds_read_b128 v[138:141], v142 offset:2048
	ds_read_b128 v[142:145], v142 offset:3072
	ds_read_b128 v[146:149], v158
	ds_read_b128 v[150:153], v158 offset:1024
	ds_read_b128 v[154:157], v158 offset:2048
	ds_read_b128 v[158:161], v158 offset:3072
	s_add_u32 s34, s34, 0xc0000
	s_addc_u32 s35, s35, 0
	s_mov_b32 m0, s39
	ds_read_b128 v[162:165], v201 offset:32768
	ds_read_b128 v[166:169], v201 offset:33792
	ds_read_b128 v[170:173], v201 offset:34816
	ds_read_b128 v[174:177], v201 offset:35840
	ds_read_b128 v[202:205], v201 offset:36864
	ds_read_b128 v[206:209], v201 offset:37888
	ds_read_b128 v[210:213], v201 offset:38912
	ds_read_b128 v[214:217], v201 offset:39936
	global_load_lds_dwordx4 v184, s[34:35]
	s_mov_b32 m0, s40
	s_nop 0
	global_load_lds_dwordx4 v180, s[34:35]
	s_waitcnt vmcnt(8)
	s_waitcnt lgkmcnt(0)
	s_barrier
	s_setprio 1
	s_waitcnt lgkmcnt(0)
	v_mfma_f32_16x16x32_bf16 v[126:129], v[130:133], v[162:165], v[126:129]
	v_mfma_f32_16x16x32_bf16 v[122:125], v[138:141], v[162:165], v[122:125]
	v_mfma_f32_16x16x32_bf16 v[114:117], v[138:141], v[170:173], v[114:117]
	v_mfma_f32_16x16x32_bf16 v[118:121], v[130:133], v[170:173], v[118:121]
	v_mfma_f32_16x16x32_bf16 v[110:113], v[130:133], v[202:205], v[110:113]
	v_mfma_f32_16x16x32_bf16 v[106:109], v[138:141], v[202:205], v[106:109]
	v_mfma_f32_16x16x32_bf16 v[98:101], v[138:141], v[210:213], v[98:101]
	v_mfma_f32_16x16x32_bf16 v[102:105], v[130:133], v[210:213], v[102:105]
	v_mfma_f32_16x16x32_bf16 v[126:129], v[134:137], v[166:169], v[126:129]
	v_mfma_f32_16x16x32_bf16 v[122:125], v[142:145], v[166:169], v[122:125]
	v_mfma_f32_16x16x32_bf16 v[114:117], v[142:145], v[174:177], v[114:117]
	v_mfma_f32_16x16x32_bf16 v[118:121], v[134:137], v[174:177], v[118:121]
	v_mfma_f32_16x16x32_bf16 v[110:113], v[134:137], v[206:209], v[110:113]
	v_mfma_f32_16x16x32_bf16 v[106:109], v[142:145], v[206:209], v[106:109]
	v_mfma_f32_16x16x32_bf16 v[98:101], v[142:145], v[214:217], v[98:101]
	v_mfma_f32_16x16x32_bf16 v[102:105], v[134:137], v[214:217], v[102:105]
	s_setprio 0
	s_setprio 1
	v_mfma_f32_16x16x32_bf16 v[94:97], v[146:149], v[162:165], v[94:97]
	v_mfma_f32_16x16x32_bf16 v[90:93], v[154:157], v[162:165], v[90:93]
	v_mfma_f32_16x16x32_bf16 v[82:85], v[154:157], v[170:173], v[82:85]
	v_mfma_f32_16x16x32_bf16 v[86:89], v[146:149], v[170:173], v[86:89]
	v_mfma_f32_16x16x32_bf16 v[78:81], v[146:149], v[202:205], v[78:81]
	v_mfma_f32_16x16x32_bf16 v[74:77], v[154:157], v[202:205], v[74:77]
	v_mfma_f32_16x16x32_bf16 v[58:61], v[154:157], v[210:213], v[58:61]
	v_mfma_f32_16x16x32_bf16 v[66:69], v[146:149], v[210:213], v[66:69]
	v_mfma_f32_16x16x32_bf16 v[94:97], v[150:153], v[166:169], v[94:97]
	v_mfma_f32_16x16x32_bf16 v[90:93], v[158:161], v[166:169], v[90:93]
	v_mfma_f32_16x16x32_bf16 v[82:85], v[158:161], v[174:177], v[82:85]
	v_mfma_f32_16x16x32_bf16 v[86:89], v[150:153], v[174:177], v[86:89]
	v_mfma_f32_16x16x32_bf16 v[78:81], v[150:153], v[206:209], v[78:81]
	v_mfma_f32_16x16x32_bf16 v[74:77], v[158:161], v[206:209], v[74:77]
	v_mfma_f32_16x16x32_bf16 v[58:61], v[158:161], v[214:217], v[58:61]
	v_mfma_f32_16x16x32_bf16 v[66:69], v[150:153], v[214:217], v[66:69]
	s_setprio 0
	s_barrier
	s_add_u32 s34, s30, 0x4000
	s_addc_u32 s35, s31, 0
	s_add_i32 s71, s71, s36
	s_mov_b32 m0, s71
	ds_read_b128 v[162:165], v201 offset:49152
	ds_read_b128 v[166:169], v201 offset:50176
	ds_read_b128 v[170:173], v201 offset:51200
	ds_read_b128 v[174:177], v201 offset:52224
	ds_read_b128 v[202:205], v201 offset:53248
	ds_read_b128 v[206:209], v201 offset:54272
	ds_read_b128 v[210:213], v201 offset:55296
	ds_read_b128 v[214:217], v201 offset:56320
	global_load_lds_dwordx4 v182, s[34:35]
	s_add_i32 m0, s71, 0x2000
	s_add_u32 s30, s30, 0xc4000
	s_addc_u32 s31, s31, 0
	global_load_lds_dwordx4 v178, s[34:35]
	s_add_i32 s34, s72, s36
	s_mov_b32 m0, s34
	s_nop 0
	global_load_lds_dwordx4 v182, s[30:31]
	s_add_i32 m0, s34, 0x2000
	s_nop 0
	global_load_lds_dwordx4 v178, s[30:31]
	s_mov_b32 m0, s42
	s_nop 0
	global_load_lds_dwordx4 v184, s[26:27]
	s_mov_b32 m0, s43
	s_nop 0
	global_load_lds_dwordx4 v180, s[26:27]
	s_waitcnt vmcnt(8)
	s_waitcnt lgkmcnt(0)
	s_barrier
	s_setprio 1
	s_waitcnt lgkmcnt(0)
	v_mfma_f32_16x16x32_bf16 v[70:73], v[130:133], v[162:165], v[70:73]
	v_mfma_f32_16x16x32_bf16 v[62:65], v[138:141], v[162:165], v[62:65]
	v_mfma_f32_16x16x32_bf16 v[50:53], v[138:141], v[170:173], v[50:53]
	v_mfma_f32_16x16x32_bf16 v[54:57], v[130:133], v[170:173], v[54:57]
	v_mfma_f32_16x16x32_bf16 v[46:49], v[130:133], v[202:205], v[46:49]
	v_mfma_f32_16x16x32_bf16 v[42:45], v[138:141], v[202:205], v[42:45]
	v_mfma_f32_16x16x32_bf16 v[34:37], v[138:141], v[210:213], v[34:37]
	v_mfma_f32_16x16x32_bf16 v[38:41], v[130:133], v[210:213], v[38:41]
	v_mfma_f32_16x16x32_bf16 v[70:73], v[134:137], v[166:169], v[70:73]
	v_mfma_f32_16x16x32_bf16 v[62:65], v[142:145], v[166:169], v[62:65]
	v_mfma_f32_16x16x32_bf16 v[50:53], v[142:145], v[174:177], v[50:53]
	v_mfma_f32_16x16x32_bf16 v[54:57], v[134:137], v[174:177], v[54:57]
	v_mfma_f32_16x16x32_bf16 v[46:49], v[134:137], v[206:209], v[46:49]
	v_mfma_f32_16x16x32_bf16 v[42:45], v[142:145], v[206:209], v[42:45]
	v_mfma_f32_16x16x32_bf16 v[34:37], v[142:145], v[214:217], v[34:37]
	v_mfma_f32_16x16x32_bf16 v[38:41], v[134:137], v[214:217], v[38:41]
	s_setprio 0
	s_setprio 1
	v_mfma_f32_16x16x32_bf16 v[30:33], v[146:149], v[162:165], v[30:33]
	v_mfma_f32_16x16x32_bf16 v[26:29], v[154:157], v[162:165], v[26:29]
	v_mfma_f32_16x16x32_bf16 v[18:21], v[154:157], v[170:173], v[18:21]
	v_mfma_f32_16x16x32_bf16 v[22:25], v[146:149], v[170:173], v[22:25]
	v_mfma_f32_16x16x32_bf16 v[14:17], v[146:149], v[202:205], v[14:17]
	v_mfma_f32_16x16x32_bf16 v[10:13], v[154:157], v[202:205], v[10:13]
	v_mfma_f32_16x16x32_bf16 v[2:5], v[154:157], v[210:213], v[2:5]
	v_mfma_f32_16x16x32_bf16 v[6:9], v[146:149], v[210:213], v[6:9]
	v_mfma_f32_16x16x32_bf16 v[30:33], v[150:153], v[166:169], v[30:33]
	v_mfma_f32_16x16x32_bf16 v[26:29], v[158:161], v[166:169], v[26:29]
	v_mfma_f32_16x16x32_bf16 v[18:21], v[158:161], v[174:177], v[18:21]
	v_mfma_f32_16x16x32_bf16 v[22:25], v[150:153], v[174:177], v[22:25]
	v_mfma_f32_16x16x32_bf16 v[14:17], v[150:153], v[206:209], v[14:17]
	v_mfma_f32_16x16x32_bf16 v[10:13], v[158:161], v[206:209], v[10:13]
	v_mfma_f32_16x16x32_bf16 v[2:5], v[158:161], v[214:217], v[2:5]
	v_mfma_f32_16x16x32_bf16 v[6:9], v[150:153], v[214:217], v[6:9]
	s_setprio 0
	s_barrier
	s_add_u32 s24, s24, 0x8000
	s_addc_u32 s25, s25, 0
	s_add_u32 s68, s68, 0x8000
	s_addc_u32 s69, s69, 0
	s_cmp_ge_u32 s70, s66
	s_mov_b32 s31, s70
	s_cbranch_scc0 .LBB0_1005
	s_and_b64 vcc, exec, s[18:19]
	s_cbranch_vccnz .LBB0_1010
	v_lshl_add_u32 v162, s65, 8, v189
	s_mov_b64 s[24:25], -1
	s_and_b64 vcc, exec, s[22:23]
	s_cbranch_vccnz .LBB0_1011

.LBB0_1088:
	ds_read_b128 v[130:133], v209
	ds_read_b128 v[134:137], v209 offset:1024
	ds_read_b128 v[138:141], v209 offset:2048
	ds_read_b128 v[142:145], v209 offset:3072
	ds_read_b128 v[146:149], v210
	ds_read_b128 v[150:153], v210 offset:1024
	ds_read_b128 v[154:157], v210 offset:2048
	ds_read_b128 v[158:161], v210 offset:3072
	s_add_u32 s38, s36, 0xfff04000
	s_addc_u32 s39, s37, -1
	s_cmp_eq_u32 s72, 60
	s_cselect_b32 s42, s35, s38
	s_cselect_b32 s43, s25, s39
	s_cselect_b32 s40, s69, s70
	s_cselect_b32 s41, s23, s71
	s_add_u32 s38, s42, 0x4000
	s_addc_u32 s39, s43, 0
	s_add_i32 m0, s47, 0xc000
	ds_read_b128 v[162:165], v211
	ds_read_b128 v[166:169], v211 offset:1024
	ds_read_b128 v[170:173], v211 offset:2048
	ds_read_b128 v[174:177], v211 offset:3072
	ds_read_b128 v[196:199], v211 offset:4096
	ds_read_b128 v[200:203], v211 offset:5120
	ds_read_b128 v[214:217], v211 offset:6144
	ds_read_b128 v[218:221], v211 offset:7168
	global_load_lds_dwordx4 v188, s[36:37]
	s_add_i32 m0, s47, 0xe000
	s_nop 0
	global_load_lds_dwordx4 v190, s[36:37]
	s_waitcnt vmcnt(8)
	s_waitcnt lgkmcnt(0)
	s_barrier
	s_setprio 1
	s_waitcnt lgkmcnt(0)
	v_mfma_f32_16x16x32_bf16 v[126:129], v[130:133], v[162:165], v[126:129]
	v_mfma_f32_16x16x32_bf16 v[122:125], v[138:141], v[162:165], v[122:125]
	v_mfma_f32_16x16x32_bf16 v[106:109], v[138:141], v[170:173], v[106:109]
	v_mfma_f32_16x16x32_bf16 v[110:113], v[130:133], v[170:173], v[110:113]
	v_mfma_f32_16x16x32_bf16 v[94:97], v[130:133], v[196:199], v[94:97]
	v_mfma_f32_16x16x32_bf16 v[90:93], v[138:141], v[196:199], v[90:93]
	v_mfma_f32_16x16x32_bf16 v[74:77], v[138:141], v[214:217], v[74:77]
	v_mfma_f32_16x16x32_bf16 v[78:81], v[130:133], v[214:217], v[78:81]
	v_mfma_f32_16x16x32_bf16 v[126:129], v[134:137], v[166:169], v[126:129]
	v_mfma_f32_16x16x32_bf16 v[122:125], v[142:145], v[166:169], v[122:125]
	v_mfma_f32_16x16x32_bf16 v[106:109], v[142:145], v[174:177], v[106:109]
	v_mfma_f32_16x16x32_bf16 v[110:113], v[134:137], v[174:177], v[110:113]
	v_mfma_f32_16x16x32_bf16 v[94:97], v[134:137], v[200:203], v[94:97]
	v_mfma_f32_16x16x32_bf16 v[90:93], v[142:145], v[200:203], v[90:93]
	v_mfma_f32_16x16x32_bf16 v[74:77], v[142:145], v[218:221], v[74:77]
	v_mfma_f32_16x16x32_bf16 v[78:81], v[134:137], v[218:221], v[78:81]
	s_setprio 0
	s_setprio 1
	v_mfma_f32_16x16x32_bf16 v[118:121], v[146:149], v[162:165], v[118:121]
	v_mfma_f32_16x16x32_bf16 v[114:117], v[154:157], v[162:165], v[114:117]
	v_mfma_f32_16x16x32_bf16 v[98:101], v[154:157], v[170:173], v[98:101]
	v_mfma_f32_16x16x32_bf16 v[102:105], v[146:149], v[170:173], v[102:105]
	v_mfma_f32_16x16x32_bf16 v[86:89], v[146:149], v[196:199], v[86:89]
	v_mfma_f32_16x16x32_bf16 v[82:85], v[154:157], v[196:199], v[82:85]
	v_mfma_f32_16x16x32_bf16 v[66:69], v[154:157], v[214:217], v[66:69]
	v_mfma_f32_16x16x32_bf16 v[70:73], v[146:149], v[214:217], v[70:73]
	v_mfma_f32_16x16x32_bf16 v[118:121], v[150:153], v[166:169], v[118:121]
	v_mfma_f32_16x16x32_bf16 v[114:117], v[158:161], v[166:169], v[114:117]
	v_mfma_f32_16x16x32_bf16 v[98:101], v[158:161], v[174:177], v[98:101]
	v_mfma_f32_16x16x32_bf16 v[102:105], v[150:153], v[174:177], v[102:105]
	v_mfma_f32_16x16x32_bf16 v[86:89], v[150:153], v[200:203], v[86:89]
	v_mfma_f32_16x16x32_bf16 v[82:85], v[158:161], v[200:203], v[82:85]
	v_mfma_f32_16x16x32_bf16 v[66:69], v[158:161], v[218:221], v[66:69]
	v_mfma_f32_16x16x32_bf16 v[70:73], v[150:153], v[218:221], v[70:73]
	s_setprio 0
	s_barrier
	s_add_i32 s73, s66, s46
	s_mov_b32 m0, s73
	ds_read_b128 v[162:165], v211 offset:16384
	ds_read_b128 v[166:169], v211 offset:17408
	ds_read_b128 v[170:173], v211 offset:18432
	ds_read_b128 v[174:177], v211 offset:19456
	ds_read_b128 v[196:199], v211 offset:20480
	ds_read_b128 v[200:203], v211 offset:21504
	ds_read_b128 v[214:217], v211 offset:22528
	ds_read_b128 v[218:221], v211 offset:23552
	global_load_lds_dwordx4 v180, s[40:41]
	s_add_i32 m0, s73, 0x2000
	s_add_u32 s74, s40, 0x100000
	s_addc_u32 s75, s41, 0
	s_add_i32 s73, s67, s46
	global_load_lds_dwordx4 v184, s[40:41]
	s_mov_b32 m0, s73
	s_nop 0
	global_load_lds_dwordx4 v180, s[74:75]
	s_add_i32 m0, s73, 0x2000
	s_nop 0
	global_load_lds_dwordx4 v184, s[74:75]
	s_mov_b32 m0, s47
	s_nop 0
	global_load_lds_dwordx4 v178, s[42:43]
	s_mov_b32 m0, s59
	s_nop 0
	global_load_lds_dwordx4 v182, s[42:43]
	s_waitcnt vmcnt(8)
	s_waitcnt lgkmcnt(0)
	s_barrier
	s_setprio 1
	s_waitcnt lgkmcnt(0)
	v_mfma_f32_16x16x32_bf16 v[62:65], v[130:133], v[162:165], v[62:65]
	v_mfma_f32_16x16x32_bf16 v[58:61], v[138:141], v[162:165], v[58:61]
	v_mfma_f32_16x16x32_bf16 v[42:45], v[138:141], v[170:173], v[42:45]
	v_mfma_f32_16x16x32_bf16 v[46:49], v[130:133], v[170:173], v[46:49]
	v_mfma_f32_16x16x32_bf16 v[30:33], v[130:133], v[196:199], v[30:33]
	v_mfma_f32_16x16x32_bf16 v[26:29], v[138:141], v[196:199], v[26:29]
	v_mfma_f32_16x16x32_bf16 v[10:13], v[138:141], v[214:217], v[10:13]
	v_mfma_f32_16x16x32_bf16 v[14:17], v[130:133], v[214:217], v[14:17]
	v_mfma_f32_16x16x32_bf16 v[62:65], v[134:137], v[166:169], v[62:65]
	v_mfma_f32_16x16x32_bf16 v[58:61], v[142:145], v[166:169], v[58:61]
	v_mfma_f32_16x16x32_bf16 v[42:45], v[142:145], v[174:177], v[42:45]
	v_mfma_f32_16x16x32_bf16 v[46:49], v[134:137], v[174:177], v[46:49]
	v_mfma_f32_16x16x32_bf16 v[30:33], v[134:137], v[200:203], v[30:33]
	v_mfma_f32_16x16x32_bf16 v[26:29], v[142:145], v[200:203], v[26:29]
	v_mfma_f32_16x16x32_bf16 v[10:13], v[142:145], v[218:221], v[10:13]
	v_mfma_f32_16x16x32_bf16 v[14:17], v[134:137], v[218:221], v[14:17]
	s_setprio 0
	s_setprio 1
	v_mfma_f32_16x16x32_bf16 v[54:57], v[146:149], v[162:165], v[54:57]
	v_mfma_f32_16x16x32_bf16 v[50:53], v[154:157], v[162:165], v[50:53]
	v_mfma_f32_16x16x32_bf16 v[34:37], v[154:157], v[170:173], v[34:37]
	v_mfma_f32_16x16x32_bf16 v[38:41], v[146:149], v[170:173], v[38:41]
	v_mfma_f32_16x16x32_bf16 v[22:25], v[146:149], v[196:199], v[22:25]
	v_mfma_f32_16x16x32_bf16 v[18:21], v[154:157], v[196:199], v[18:21]
	v_mfma_f32_16x16x32_bf16 v[2:5], v[154:157], v[214:217], v[2:5]
	v_mfma_f32_16x16x32_bf16 v[6:9], v[146:149], v[214:217], v[6:9]
	v_mfma_f32_16x16x32_bf16 v[54:57], v[150:153], v[166:169], v[54:57]
	v_mfma_f32_16x16x32_bf16 v[50:53], v[158:161], v[166:169], v[50:53]
	v_mfma_f32_16x16x32_bf16 v[34:37], v[158:161], v[174:177], v[34:37]
	v_mfma_f32_16x16x32_bf16 v[38:41], v[150:153], v[174:177], v[38:41]
	v_mfma_f32_16x16x32_bf16 v[22:25], v[150:153], v[200:203], v[22:25]
	v_mfma_f32_16x16x32_bf16 v[18:21], v[158:161], v[200:203], v[18:21]
	v_mfma_f32_16x16x32_bf16 v[2:5], v[158:161], v[218:221], v[2:5]
	v_mfma_f32_16x16x32_bf16 v[6:9], v[150:153], v[218:221], v[6:9]
	s_setprio 0
	s_barrier
	s_add_i32 s73, 0, 0x18000
	s_add_i32 s74, 0, 0x1c000
	v_add_u32_e32 v142, s73, v208
	v_add_u32_e32 v158, s74, v208
	ds_read_b128 v[130:133], v142
	ds_read_b128 v[134:137], v142 offset:1024
	ds_read_b128 v[138:141], v142 offset:2048
	ds_read_b128 v[142:145], v142 offset:3072
	ds_read_b128 v[146:149], v158
	ds_read_b128 v[150:153], v158 offset:1024
	ds_read_b128 v[154:157], v158 offset:2048
	ds_read_b128 v[158:161], v158 offset:3072
	s_add_u32 s42, s42, 0x100000
	s_addc_u32 s43, s43, 0
	s_mov_b32 m0, s60
	ds_read_b128 v[162:165], v211 offset:32768
	ds_read_b128 v[166:169], v211 offset:33792
	ds_read_b128 v[170:173], v211 offset:34816
	ds_read_b128 v[174:177], v211 offset:35840
	ds_read_b128 v[196:199], v211 offset:36864
	ds_read_b128 v[200:203], v211 offset:37888
	ds_read_b128 v[214:217], v211 offset:38912
	ds_read_b128 v[218:221], v211 offset:39936
	global_load_lds_dwordx4 v178, s[42:43]
	s_mov_b32 m0, s61
	s_nop 0
	global_load_lds_dwordx4 v182, s[42:43]
	s_waitcnt vmcnt(8)
	s_waitcnt lgkmcnt(0)
	s_barrier
	s_setprio 1
	s_waitcnt lgkmcnt(0)
	v_mfma_f32_16x16x32_bf16 v[126:129], v[130:133], v[162:165], v[126:129]
	v_mfma_f32_16x16x32_bf16 v[122:125], v[138:141], v[162:165], v[122:125]
	v_mfma_f32_16x16x32_bf16 v[106:109], v[138:141], v[170:173], v[106:109]
	v_mfma_f32_16x16x32_bf16 v[110:113], v[130:133], v[170:173], v[110:113]
	v_mfma_f32_16x16x32_bf16 v[94:97], v[130:133], v[196:199], v[94:97]
	v_mfma_f32_16x16x32_bf16 v[90:93], v[138:141], v[196:199], v[90:93]
	v_mfma_f32_16x16x32_bf16 v[74:77], v[138:141], v[214:217], v[74:77]
	v_mfma_f32_16x16x32_bf16 v[78:81], v[130:133], v[214:217], v[78:81]
	v_mfma_f32_16x16x32_bf16 v[126:129], v[134:137], v[166:169], v[126:129]
	v_mfma_f32_16x16x32_bf16 v[122:125], v[142:145], v[166:169], v[122:125]
	v_mfma_f32_16x16x32_bf16 v[106:109], v[142:145], v[174:177], v[106:109]
	v_mfma_f32_16x16x32_bf16 v[110:113], v[134:137], v[174:177], v[110:113]
	v_mfma_f32_16x16x32_bf16 v[94:97], v[134:137], v[200:203], v[94:97]
	v_mfma_f32_16x16x32_bf16 v[90:93], v[142:145], v[200:203], v[90:93]
	v_mfma_f32_16x16x32_bf16 v[74:77], v[142:145], v[218:221], v[74:77]
	v_mfma_f32_16x16x32_bf16 v[78:81], v[134:137], v[218:221], v[78:81]
	s_setprio 0
	s_setprio 1
	v_mfma_f32_16x16x32_bf16 v[118:121], v[146:149], v[162:165], v[118:121]
	v_mfma_f32_16x16x32_bf16 v[114:117], v[154:157], v[162:165], v[114:117]
	v_mfma_f32_16x16x32_bf16 v[98:101], v[154:157], v[170:173], v[98:101]
	v_mfma_f32_16x16x32_bf16 v[102:105], v[146:149], v[170:173], v[102:105]
	v_mfma_f32_16x16x32_bf16 v[86:89], v[146:149], v[196:199], v[86:89]
	v_mfma_f32_16x16x32_bf16 v[82:85], v[154:157], v[196:199], v[82:85]
	v_mfma_f32_16x16x32_bf16 v[66:69], v[154:157], v[214:217], v[66:69]
	v_mfma_f32_16x16x32_bf16 v[70:73], v[146:149], v[214:217], v[70:73]
	v_mfma_f32_16x16x32_bf16 v[118:121], v[150:153], v[166:169], v[118:121]
	v_mfma_f32_16x16x32_bf16 v[114:117], v[158:161], v[166:169], v[114:117]
	v_mfma_f32_16x16x32_bf16 v[98:101], v[158:161], v[174:177], v[98:101]
	v_mfma_f32_16x16x32_bf16 v[102:105], v[150:153], v[174:177], v[102:105]
	v_mfma_f32_16x16x32_bf16 v[86:89], v[150:153], v[200:203], v[86:89]
	v_mfma_f32_16x16x32_bf16 v[82:85], v[158:161], v[200:203], v[82:85]
	v_mfma_f32_16x16x32_bf16 v[66:69], v[158:161], v[218:221], v[66:69]
	v_mfma_f32_16x16x32_bf16 v[70:73], v[150:153], v[218:221], v[70:73]
	s_setprio 0
	s_barrier
	s_add_u32 s42, s40, 0x4000
	s_addc_u32 s43, s41, 0
	s_add_i32 s73, s73, s46
	s_mov_b32 m0, s73
	ds_read_b128 v[162:165], v211 offset:49152
	ds_read_b128 v[166:169], v211 offset:50176
	ds_read_b128 v[170:173], v211 offset:51200
	ds_read_b128 v[174:177], v211 offset:52224
	ds_read_b128 v[196:199], v211 offset:53248
	ds_read_b128 v[200:203], v211 offset:54272
	ds_read_b128 v[214:217], v211 offset:55296
	ds_read_b128 v[218:221], v211 offset:56320
	global_load_lds_dwordx4 v180, s[42:43]
	s_add_i32 m0, s73, 0x2000
	s_add_u32 s40, s40, 0x104000
	s_addc_u32 s41, s41, 0
	global_load_lds_dwordx4 v184, s[42:43]
	s_add_i32 s42, s74, s46
	s_mov_b32 m0, s42
	s_nop 0
	global_load_lds_dwordx4 v180, s[40:41]
	s_add_i32 m0, s42, 0x2000
	s_nop 0
	global_load_lds_dwordx4 v184, s[40:41]
	s_mov_b32 m0, s64
	s_nop 0
	global_load_lds_dwordx4 v178, s[38:39]
	s_mov_b32 m0, s65
	s_nop 0
	global_load_lds_dwordx4 v182, s[38:39]
	s_waitcnt vmcnt(8)
	s_waitcnt lgkmcnt(0)
	s_barrier
	s_setprio 1
	s_waitcnt lgkmcnt(0)
	v_mfma_f32_16x16x32_bf16 v[62:65], v[130:133], v[162:165], v[62:65]
	v_mfma_f32_16x16x32_bf16 v[58:61], v[138:141], v[162:165], v[58:61]
	v_mfma_f32_16x16x32_bf16 v[42:45], v[138:141], v[170:173], v[42:45]
	v_mfma_f32_16x16x32_bf16 v[46:49], v[130:133], v[170:173], v[46:49]
	v_mfma_f32_16x16x32_bf16 v[30:33], v[130:133], v[196:199], v[30:33]
	v_mfma_f32_16x16x32_bf16 v[26:29], v[138:141], v[196:199], v[26:29]
	v_mfma_f32_16x16x32_bf16 v[10:13], v[138:141], v[214:217], v[10:13]
	v_mfma_f32_16x16x32_bf16 v[14:17], v[130:133], v[214:217], v[14:17]
	v_mfma_f32_16x16x32_bf16 v[62:65], v[134:137], v[166:169], v[62:65]
	v_mfma_f32_16x16x32_bf16 v[58:61], v[142:145], v[166:169], v[58:61]
	v_mfma_f32_16x16x32_bf16 v[42:45], v[142:145], v[174:177], v[42:45]
	v_mfma_f32_16x16x32_bf16 v[46:49], v[134:137], v[174:177], v[46:49]
	v_mfma_f32_16x16x32_bf16 v[30:33], v[134:137], v[200:203], v[30:33]
	v_mfma_f32_16x16x32_bf16 v[26:29], v[142:145], v[200:203], v[26:29]
	v_mfma_f32_16x16x32_bf16 v[10:13], v[142:145], v[218:221], v[10:13]
	v_mfma_f32_16x16x32_bf16 v[14:17], v[134:137], v[218:221], v[14:17]
	s_setprio 0
	s_setprio 1
	v_mfma_f32_16x16x32_bf16 v[54:57], v[146:149], v[162:165], v[54:57]
	v_mfma_f32_16x16x32_bf16 v[50:53], v[154:157], v[162:165], v[50:53]
	v_mfma_f32_16x16x32_bf16 v[34:37], v[154:157], v[170:173], v[34:37]
	v_mfma_f32_16x16x32_bf16 v[38:41], v[146:149], v[170:173], v[38:41]
	v_mfma_f32_16x16x32_bf16 v[22:25], v[146:149], v[196:199], v[22:25]
	v_mfma_f32_16x16x32_bf16 v[18:21], v[154:157], v[196:199], v[18:21]
	v_mfma_f32_16x16x32_bf16 v[2:5], v[154:157], v[214:217], v[2:5]
	v_mfma_f32_16x16x32_bf16 v[6:9], v[146:149], v[214:217], v[6:9]
	v_mfma_f32_16x16x32_bf16 v[54:57], v[150:153], v[166:169], v[54:57]
	v_mfma_f32_16x16x32_bf16 v[50:53], v[158:161], v[166:169], v[50:53]
	v_mfma_f32_16x16x32_bf16 v[34:37], v[158:161], v[174:177], v[34:37]
	v_mfma_f32_16x16x32_bf16 v[38:41], v[150:153], v[174:177], v[38:41]
	v_mfma_f32_16x16x32_bf16 v[22:25], v[150:153], v[200:203], v[22:25]
	v_mfma_f32_16x16x32_bf16 v[18:21], v[158:161], v[200:203], v[18:21]
	v_mfma_f32_16x16x32_bf16 v[2:5], v[158:161], v[218:221], v[2:5]
	v_mfma_f32_16x16x32_bf16 v[6:9], v[150:153], v[218:221], v[6:9]
	s_setprio 0
	s_barrier
	s_add_i32 s72, s72, 2
	s_add_u32 s36, s36, 0x8000
	s_addc_u32 s37, s37, 0
	s_add_u32 s70, s70, 0x8000
	s_addc_u32 s71, s71, 0
	s_cmp_gt_u32 s72, 61
	s_cbranch_scc0 .LBB0_1088
	s_and_b64 vcc, exec, s[20:21]
	s_cbranch_vccz .LBB0_1091
	s_barrier

.LBB0_1215:
	ds_read_b128 v[160:163], v154
	ds_read_b128 v[164:167], v154 offset:1024
	ds_read_b128 v[168:171], v154 offset:2048
	ds_read_b128 v[172:175], v154 offset:3072
	ds_read_b128 v[176:179], v155
	ds_read_b128 v[180:183], v155 offset:1024
	ds_read_b128 v[184:187], v155 offset:2048
	ds_read_b128 v[188:191], v155 offset:3072
	s_add_u32 s30, s28, 0xfff04000
	s_addc_u32 s31, s29, -1
	s_cmp_eq_u32 s61, 60
	s_cselect_b32 s36, s56, s30
	s_cselect_b32 s37, s21, s31
	s_cselect_b32 s34, s57, s59
	s_cselect_b32 s35, s19, s60
	s_add_u32 s30, s36, 0x4000
	s_addc_u32 s31, s37, 0
	s_add_i32 m0, s39, 0xc000
	ds_read_b128 v[192:195], v156
	ds_read_b128 v[196:199], v156 offset:1024
	ds_read_b128 v[200:203], v156 offset:2048
	ds_read_b128 v[204:207], v156 offset:3072
	ds_read_b128 v[208:211], v156 offset:4096
	ds_read_b128 v[212:215], v156 offset:5120
	ds_read_b128 v[216:219], v156 offset:6144
	ds_read_b128 v[220:223], v156 offset:7168
	global_load_lds_dwordx4 v140, s[28:29]
	s_add_i32 m0, s39, 0xe000
	s_nop 0
	global_load_lds_dwordx4 v142, s[28:29]
	s_waitcnt vmcnt(8)
	s_waitcnt lgkmcnt(0)
	s_barrier
	s_setprio 1
	s_waitcnt lgkmcnt(0)
	v_mfma_f32_16x16x32_bf16 v[126:129], v[160:163], v[192:195], v[126:129]
	v_mfma_f32_16x16x32_bf16 v[122:125], v[168:171], v[192:195], v[122:125]
	v_mfma_f32_16x16x32_bf16 v[106:109], v[168:171], v[200:203], v[106:109]
	v_mfma_f32_16x16x32_bf16 v[110:113], v[160:163], v[200:203], v[110:113]
	v_mfma_f32_16x16x32_bf16 v[94:97], v[160:163], v[208:211], v[94:97]
	v_mfma_f32_16x16x32_bf16 v[90:93], v[168:171], v[208:211], v[90:93]
	v_mfma_f32_16x16x32_bf16 v[74:77], v[168:171], v[216:219], v[74:77]
	v_mfma_f32_16x16x32_bf16 v[78:81], v[160:163], v[216:219], v[78:81]
	v_mfma_f32_16x16x32_bf16 v[126:129], v[164:167], v[196:199], v[126:129]
	v_mfma_f32_16x16x32_bf16 v[122:125], v[172:175], v[196:199], v[122:125]
	v_mfma_f32_16x16x32_bf16 v[106:109], v[172:175], v[204:207], v[106:109]
	v_mfma_f32_16x16x32_bf16 v[110:113], v[164:167], v[204:207], v[110:113]
	v_mfma_f32_16x16x32_bf16 v[94:97], v[164:167], v[212:215], v[94:97]
	v_mfma_f32_16x16x32_bf16 v[90:93], v[172:175], v[212:215], v[90:93]
	v_mfma_f32_16x16x32_bf16 v[74:77], v[172:175], v[220:223], v[74:77]
	v_mfma_f32_16x16x32_bf16 v[78:81], v[164:167], v[220:223], v[78:81]
	s_setprio 0
	s_setprio 1
	v_mfma_f32_16x16x32_bf16 v[118:121], v[176:179], v[192:195], v[118:121]
	v_mfma_f32_16x16x32_bf16 v[114:117], v[184:187], v[192:195], v[114:117]
	v_mfma_f32_16x16x32_bf16 v[98:101], v[184:187], v[200:203], v[98:101]
	v_mfma_f32_16x16x32_bf16 v[102:105], v[176:179], v[200:203], v[102:105]
	v_mfma_f32_16x16x32_bf16 v[86:89], v[176:179], v[208:211], v[86:89]
	v_mfma_f32_16x16x32_bf16 v[82:85], v[184:187], v[208:211], v[82:85]
	v_mfma_f32_16x16x32_bf16 v[66:69], v[184:187], v[216:219], v[66:69]
	v_mfma_f32_16x16x32_bf16 v[70:73], v[176:179], v[216:219], v[70:73]
	v_mfma_f32_16x16x32_bf16 v[118:121], v[180:183], v[196:199], v[118:121]
	v_mfma_f32_16x16x32_bf16 v[114:117], v[188:191], v[196:199], v[114:117]
	v_mfma_f32_16x16x32_bf16 v[98:101], v[188:191], v[204:207], v[98:101]
	v_mfma_f32_16x16x32_bf16 v[102:105], v[180:183], v[204:207], v[102:105]
	v_mfma_f32_16x16x32_bf16 v[86:89], v[180:183], v[212:215], v[86:89]
	v_mfma_f32_16x16x32_bf16 v[82:85], v[188:191], v[212:215], v[82:85]
	v_mfma_f32_16x16x32_bf16 v[66:69], v[188:191], v[220:223], v[66:69]
	v_mfma_f32_16x16x32_bf16 v[70:73], v[180:183], v[220:223], v[70:73]
	s_setprio 0
	s_barrier
	s_add_i32 s62, s47, s38
	s_mov_b32 m0, s62
	ds_read_b128 v[192:195], v156 offset:16384
	ds_read_b128 v[196:199], v156 offset:17408
	ds_read_b128 v[200:203], v156 offset:18432
	ds_read_b128 v[204:207], v156 offset:19456
	ds_read_b128 v[208:211], v156 offset:20480
	ds_read_b128 v[212:215], v156 offset:21504
	ds_read_b128 v[216:219], v156 offset:22528
	ds_read_b128 v[220:223], v156 offset:23552
	global_load_lds_dwordx4 v134, s[34:35]
	s_add_i32 m0, s62, 0x2000
	s_add_u32 s62, s34, 0x100000
	s_addc_u32 s63, s35, 0
	s_add_i32 s64, s54, s38
	global_load_lds_dwordx4 v130, s[34:35]
	s_mov_b32 m0, s64
	s_nop 0
	global_load_lds_dwordx4 v134, s[62:63]
	s_add_i32 m0, s64, 0x2000
	s_nop 0
	global_load_lds_dwordx4 v130, s[62:63]
	s_mov_b32 m0, s39
	s_nop 0
	global_load_lds_dwordx4 v136, s[36:37]
	s_mov_b32 m0, s40
	s_nop 0
	global_load_lds_dwordx4 v132, s[36:37]
	s_waitcnt vmcnt(8)
	s_waitcnt lgkmcnt(0)
	s_barrier
	s_setprio 1
	s_waitcnt lgkmcnt(0)
	v_mfma_f32_16x16x32_bf16 v[62:65], v[160:163], v[192:195], v[62:65]
	v_mfma_f32_16x16x32_bf16 v[58:61], v[168:171], v[192:195], v[58:61]
	v_mfma_f32_16x16x32_bf16 v[42:45], v[168:171], v[200:203], v[42:45]
	v_mfma_f32_16x16x32_bf16 v[46:49], v[160:163], v[200:203], v[46:49]
	v_mfma_f32_16x16x32_bf16 v[30:33], v[160:163], v[208:211], v[30:33]
	v_mfma_f32_16x16x32_bf16 v[26:29], v[168:171], v[208:211], v[26:29]
	v_mfma_f32_16x16x32_bf16 v[10:13], v[168:171], v[216:219], v[10:13]
	v_mfma_f32_16x16x32_bf16 v[14:17], v[160:163], v[216:219], v[14:17]
	v_mfma_f32_16x16x32_bf16 v[62:65], v[164:167], v[196:199], v[62:65]
	v_mfma_f32_16x16x32_bf16 v[58:61], v[172:175], v[196:199], v[58:61]
	v_mfma_f32_16x16x32_bf16 v[42:45], v[172:175], v[204:207], v[42:45]
	v_mfma_f32_16x16x32_bf16 v[46:49], v[164:167], v[204:207], v[46:49]
	v_mfma_f32_16x16x32_bf16 v[30:33], v[164:167], v[212:215], v[30:33]
	v_mfma_f32_16x16x32_bf16 v[26:29], v[172:175], v[212:215], v[26:29]
	v_mfma_f32_16x16x32_bf16 v[10:13], v[172:175], v[220:223], v[10:13]
	v_mfma_f32_16x16x32_bf16 v[14:17], v[164:167], v[220:223], v[14:17]
	s_setprio 0
	s_setprio 1
	v_mfma_f32_16x16x32_bf16 v[54:57], v[176:179], v[192:195], v[54:57]
	v_mfma_f32_16x16x32_bf16 v[50:53], v[184:187], v[192:195], v[50:53]
	v_mfma_f32_16x16x32_bf16 v[34:37], v[184:187], v[200:203], v[34:37]
	v_mfma_f32_16x16x32_bf16 v[38:41], v[176:179], v[200:203], v[38:41]
	v_mfma_f32_16x16x32_bf16 v[22:25], v[176:179], v[208:211], v[22:25]
	v_mfma_f32_16x16x32_bf16 v[18:21], v[184:187], v[208:211], v[18:21]
	v_mfma_f32_16x16x32_bf16 v[2:5], v[184:187], v[216:219], v[2:5]
	v_mfma_f32_16x16x32_bf16 v[6:9], v[176:179], v[216:219], v[6:9]
	v_mfma_f32_16x16x32_bf16 v[54:57], v[180:183], v[196:199], v[54:57]
	v_mfma_f32_16x16x32_bf16 v[50:53], v[188:191], v[196:199], v[50:53]
	v_mfma_f32_16x16x32_bf16 v[34:37], v[188:191], v[204:207], v[34:37]
	v_mfma_f32_16x16x32_bf16 v[38:41], v[180:183], v[204:207], v[38:41]
	v_mfma_f32_16x16x32_bf16 v[22:25], v[180:183], v[212:215], v[22:25]
	v_mfma_f32_16x16x32_bf16 v[18:21], v[188:191], v[212:215], v[18:21]
	v_mfma_f32_16x16x32_bf16 v[2:5], v[188:191], v[220:223], v[2:5]
	v_mfma_f32_16x16x32_bf16 v[6:9], v[180:183], v[220:223], v[6:9]
	s_setprio 0
	s_barrier
	s_add_i32 s62, 0, 0x18000
	v_add_u32_e32 v138, s62, v153
	s_add_i32 s63, 0, 0x1c000
	ds_read_b128 v[160:163], v138
	ds_read_b128 v[164:167], v138 offset:1024
	ds_read_b128 v[168:171], v138 offset:2048
	ds_read_b128 v[172:175], v138 offset:3072
	v_add_u32_e32 v138, s63, v153
	ds_read_b128 v[176:179], v138
	ds_read_b128 v[180:183], v138 offset:1024
	ds_read_b128 v[184:187], v138 offset:2048
	ds_read_b128 v[188:191], v138 offset:3072
	s_add_u32 s36, s36, 0x100000
	s_addc_u32 s37, s37, 0
	s_mov_b32 m0, s41
	ds_read_b128 v[192:195], v156 offset:32768
	ds_read_b128 v[196:199], v156 offset:33792
	ds_read_b128 v[200:203], v156 offset:34816
	ds_read_b128 v[204:207], v156 offset:35840
	ds_read_b128 v[208:211], v156 offset:36864
	ds_read_b128 v[212:215], v156 offset:37888
	ds_read_b128 v[216:219], v156 offset:38912
	ds_read_b128 v[220:223], v156 offset:39936
	global_load_lds_dwordx4 v136, s[36:37]
	s_mov_b32 m0, s42
	s_nop 0
	global_load_lds_dwordx4 v132, s[36:37]
	s_waitcnt vmcnt(8)
	s_waitcnt lgkmcnt(0)
	s_barrier
	s_setprio 1
	s_waitcnt lgkmcnt(0)
	v_mfma_f32_16x16x32_bf16 v[126:129], v[160:163], v[192:195], v[126:129]
	v_mfma_f32_16x16x32_bf16 v[122:125], v[168:171], v[192:195], v[122:125]
	v_mfma_f32_16x16x32_bf16 v[106:109], v[168:171], v[200:203], v[106:109]
	v_mfma_f32_16x16x32_bf16 v[110:113], v[160:163], v[200:203], v[110:113]
	v_mfma_f32_16x16x32_bf16 v[94:97], v[160:163], v[208:211], v[94:97]
	v_mfma_f32_16x16x32_bf16 v[90:93], v[168:171], v[208:211], v[90:93]
	v_mfma_f32_16x16x32_bf16 v[74:77], v[168:171], v[216:219], v[74:77]
	v_mfma_f32_16x16x32_bf16 v[78:81], v[160:163], v[216:219], v[78:81]
	v_mfma_f32_16x16x32_bf16 v[126:129], v[164:167], v[196:199], v[126:129]
	v_mfma_f32_16x16x32_bf16 v[122:125], v[172:175], v[196:199], v[122:125]
	v_mfma_f32_16x16x32_bf16 v[106:109], v[172:175], v[204:207], v[106:109]
	v_mfma_f32_16x16x32_bf16 v[110:113], v[164:167], v[204:207], v[110:113]
	v_mfma_f32_16x16x32_bf16 v[94:97], v[164:167], v[212:215], v[94:97]
	v_mfma_f32_16x16x32_bf16 v[90:93], v[172:175], v[212:215], v[90:93]
	v_mfma_f32_16x16x32_bf16 v[74:77], v[172:175], v[220:223], v[74:77]
	v_mfma_f32_16x16x32_bf16 v[78:81], v[164:167], v[220:223], v[78:81]
	s_setprio 0
	s_setprio 1
	v_mfma_f32_16x16x32_bf16 v[118:121], v[176:179], v[192:195], v[118:121]
	v_mfma_f32_16x16x32_bf16 v[114:117], v[184:187], v[192:195], v[114:117]
	v_mfma_f32_16x16x32_bf16 v[98:101], v[184:187], v[200:203], v[98:101]
	v_mfma_f32_16x16x32_bf16 v[102:105], v[176:179], v[200:203], v[102:105]
	v_mfma_f32_16x16x32_bf16 v[86:89], v[176:179], v[208:211], v[86:89]
	v_mfma_f32_16x16x32_bf16 v[82:85], v[184:187], v[208:211], v[82:85]
	v_mfma_f32_16x16x32_bf16 v[66:69], v[184:187], v[216:219], v[66:69]
	v_mfma_f32_16x16x32_bf16 v[70:73], v[176:179], v[216:219], v[70:73]
	v_mfma_f32_16x16x32_bf16 v[118:121], v[180:183], v[196:199], v[118:121]
	v_mfma_f32_16x16x32_bf16 v[114:117], v[188:191], v[196:199], v[114:117]
	v_mfma_f32_16x16x32_bf16 v[98:101], v[188:191], v[204:207], v[98:101]
	v_mfma_f32_16x16x32_bf16 v[102:105], v[180:183], v[204:207], v[102:105]
	v_mfma_f32_16x16x32_bf16 v[86:89], v[180:183], v[212:215], v[86:89]
	v_mfma_f32_16x16x32_bf16 v[82:85], v[188:191], v[212:215], v[82:85]
	v_mfma_f32_16x16x32_bf16 v[66:69], v[188:191], v[220:223], v[66:69]
	v_mfma_f32_16x16x32_bf16 v[70:73], v[180:183], v[220:223], v[70:73]
	s_setprio 0
	s_barrier
	s_add_u32 s36, s34, 0x4000
	s_addc_u32 s37, s35, 0
	s_add_i32 s62, s62, s38
	s_mov_b32 m0, s62
	ds_read_b128 v[192:195], v156 offset:49152
	ds_read_b128 v[196:199], v156 offset:50176
	ds_read_b128 v[200:203], v156 offset:51200
	ds_read_b128 v[204:207], v156 offset:52224
	ds_read_b128 v[208:211], v156 offset:53248
	ds_read_b128 v[212:215], v156 offset:54272
	ds_read_b128 v[216:219], v156 offset:55296
	ds_read_b128 v[220:223], v156 offset:56320
	global_load_lds_dwordx4 v134, s[36:37]
	s_add_i32 m0, s62, 0x2000
	s_add_u32 s34, s34, 0x104000
	s_addc_u32 s35, s35, 0
	global_load_lds_dwordx4 v130, s[36:37]
	s_add_i32 s36, s63, s38
	s_mov_b32 m0, s36
	s_nop 0
	global_load_lds_dwordx4 v134, s[34:35]
	s_add_i32 m0, s36, 0x2000
	s_nop 0
	global_load_lds_dwordx4 v130, s[34:35]
	s_mov_b32 m0, s45
	s_nop 0
	global_load_lds_dwordx4 v136, s[30:31]
	s_mov_b32 m0, s46
	s_nop 0
	global_load_lds_dwordx4 v132, s[30:31]
	s_waitcnt vmcnt(8)
	s_waitcnt lgkmcnt(0)
	s_barrier
	s_setprio 1
	s_waitcnt lgkmcnt(0)
	v_mfma_f32_16x16x32_bf16 v[62:65], v[160:163], v[192:195], v[62:65]
	v_mfma_f32_16x16x32_bf16 v[58:61], v[168:171], v[192:195], v[58:61]
	v_mfma_f32_16x16x32_bf16 v[42:45], v[168:171], v[200:203], v[42:45]
	v_mfma_f32_16x16x32_bf16 v[46:49], v[160:163], v[200:203], v[46:49]
	v_mfma_f32_16x16x32_bf16 v[30:33], v[160:163], v[208:211], v[30:33]
	v_mfma_f32_16x16x32_bf16 v[26:29], v[168:171], v[208:211], v[26:29]
	v_mfma_f32_16x16x32_bf16 v[10:13], v[168:171], v[216:219], v[10:13]
	v_mfma_f32_16x16x32_bf16 v[14:17], v[160:163], v[216:219], v[14:17]
	v_mfma_f32_16x16x32_bf16 v[62:65], v[164:167], v[196:199], v[62:65]
	v_mfma_f32_16x16x32_bf16 v[58:61], v[172:175], v[196:199], v[58:61]
	v_mfma_f32_16x16x32_bf16 v[42:45], v[172:175], v[204:207], v[42:45]
	v_mfma_f32_16x16x32_bf16 v[46:49], v[164:167], v[204:207], v[46:49]
	v_mfma_f32_16x16x32_bf16 v[30:33], v[164:167], v[212:215], v[30:33]
	v_mfma_f32_16x16x32_bf16 v[26:29], v[172:175], v[212:215], v[26:29]
	v_mfma_f32_16x16x32_bf16 v[10:13], v[172:175], v[220:223], v[10:13]
	v_mfma_f32_16x16x32_bf16 v[14:17], v[164:167], v[220:223], v[14:17]
	s_setprio 0
	s_setprio 1
	v_mfma_f32_16x16x32_bf16 v[54:57], v[176:179], v[192:195], v[54:57]
	v_mfma_f32_16x16x32_bf16 v[50:53], v[184:187], v[192:195], v[50:53]
	v_mfma_f32_16x16x32_bf16 v[34:37], v[184:187], v[200:203], v[34:37]
	v_mfma_f32_16x16x32_bf16 v[38:41], v[176:179], v[200:203], v[38:41]
	v_mfma_f32_16x16x32_bf16 v[22:25], v[176:179], v[208:211], v[22:25]
	v_mfma_f32_16x16x32_bf16 v[18:21], v[184:187], v[208:211], v[18:21]
	v_mfma_f32_16x16x32_bf16 v[2:5], v[184:187], v[216:219], v[2:5]
	v_mfma_f32_16x16x32_bf16 v[6:9], v[176:179], v[216:219], v[6:9]
	v_mfma_f32_16x16x32_bf16 v[54:57], v[180:183], v[196:199], v[54:57]
	v_mfma_f32_16x16x32_bf16 v[50:53], v[188:191], v[196:199], v[50:53]
	v_mfma_f32_16x16x32_bf16 v[34:37], v[188:191], v[204:207], v[34:37]
	v_mfma_f32_16x16x32_bf16 v[38:41], v[180:183], v[204:207], v[38:41]
	v_mfma_f32_16x16x32_bf16 v[22:25], v[180:183], v[212:215], v[22:25]
	v_mfma_f32_16x16x32_bf16 v[18:21], v[188:191], v[212:215], v[18:21]
	v_mfma_f32_16x16x32_bf16 v[2:5], v[188:191], v[220:223], v[2:5]
	v_mfma_f32_16x16x32_bf16 v[6:9], v[180:183], v[220:223], v[6:9]
	s_setprio 0
	s_barrier
	s_add_i32 s61, s61, 2
	s_add_u32 s28, s28, 0x8000
	s_addc_u32 s29, s29, 0
	s_add_u32 s59, s59, 0x8000
	s_addc_u32 s60, s60, 0
	s_cmp_gt_u32 s61, 61
	s_cbranch_scc0 .LBB0_1215
	s_and_b64 vcc, exec, s[16:17]
	s_cbranch_vccz .LBB0_1218
	s_barrier

.LBB0_1292:
	ds_read_b128 v[130:133], v206
	ds_read_b128 v[134:137], v206 offset:1024
	ds_read_b128 v[138:141], v206 offset:2048
	ds_read_b128 v[142:145], v206 offset:3072
	ds_read_b128 v[146:149], v207
	ds_read_b128 v[150:153], v207 offset:1024
	ds_read_b128 v[176:179], v207 offset:2048
	ds_read_b128 v[180:183], v207 offset:3072
	s_add_u32 s42, s40, 0xffc04000
	s_addc_u32 s43, s41, -1
	s_cmpk_eq_i32 s66, 0xfc
	s_cselect_b32 s46, s29, s42
	s_cselect_b32 s47, s14, s43
	s_cselect_b32 s44, s37, s39
	s_cselect_b32 s45, s27, s65
	s_add_u32 s42, s46, 0x4000
	s_addc_u32 s43, s47, 0
	s_add_i32 m0, s53, 0xc000
	ds_read_b128 v[184:187], v208
	ds_read_b128 v[188:191], v208 offset:1024
	ds_read_b128 v[192:195], v208 offset:2048
	ds_read_b128 v[196:199], v208 offset:3072
	ds_read_b128 v[210:213], v208 offset:4096
	ds_read_b128 v[214:217], v208 offset:5120
	ds_read_b128 v[218:221], v208 offset:6144
	ds_read_b128 v[222:225], v208 offset:7168
	global_load_lds_dwordx4 v166, s[40:41]
	s_add_i32 m0, s53, 0xe000
	s_nop 0
	global_load_lds_dwordx4 v168, s[40:41]
	s_waitcnt vmcnt(8)
	s_waitcnt lgkmcnt(0)
	s_barrier
	s_setprio 1
	s_waitcnt lgkmcnt(0)
	v_mfma_f32_16x16x32_bf16 v[126:129], v[130:133], v[184:187], v[126:129]
	v_mfma_f32_16x16x32_bf16 v[122:125], v[138:141], v[184:187], v[122:125]
	v_mfma_f32_16x16x32_bf16 v[106:109], v[138:141], v[192:195], v[106:109]
	v_mfma_f32_16x16x32_bf16 v[110:113], v[130:133], v[192:195], v[110:113]
	v_mfma_f32_16x16x32_bf16 v[94:97], v[130:133], v[210:213], v[94:97]
	v_mfma_f32_16x16x32_bf16 v[90:93], v[138:141], v[210:213], v[90:93]
	v_mfma_f32_16x16x32_bf16 v[74:77], v[138:141], v[218:221], v[74:77]
	v_mfma_f32_16x16x32_bf16 v[78:81], v[130:133], v[218:221], v[78:81]
	v_mfma_f32_16x16x32_bf16 v[126:129], v[134:137], v[188:191], v[126:129]
	v_mfma_f32_16x16x32_bf16 v[122:125], v[142:145], v[188:191], v[122:125]
	v_mfma_f32_16x16x32_bf16 v[106:109], v[142:145], v[196:199], v[106:109]
	v_mfma_f32_16x16x32_bf16 v[110:113], v[134:137], v[196:199], v[110:113]
	v_mfma_f32_16x16x32_bf16 v[94:97], v[134:137], v[214:217], v[94:97]
	v_mfma_f32_16x16x32_bf16 v[90:93], v[142:145], v[214:217], v[90:93]
	v_mfma_f32_16x16x32_bf16 v[74:77], v[142:145], v[222:225], v[74:77]
	v_mfma_f32_16x16x32_bf16 v[78:81], v[134:137], v[222:225], v[78:81]
	s_setprio 0
	s_setprio 1
	v_mfma_f32_16x16x32_bf16 v[118:121], v[146:149], v[184:187], v[118:121]
	v_mfma_f32_16x16x32_bf16 v[114:117], v[176:179], v[184:187], v[114:117]
	v_mfma_f32_16x16x32_bf16 v[98:101], v[176:179], v[192:195], v[98:101]
	v_mfma_f32_16x16x32_bf16 v[102:105], v[146:149], v[192:195], v[102:105]
	v_mfma_f32_16x16x32_bf16 v[86:89], v[146:149], v[210:213], v[86:89]
	v_mfma_f32_16x16x32_bf16 v[82:85], v[176:179], v[210:213], v[82:85]
	v_mfma_f32_16x16x32_bf16 v[66:69], v[176:179], v[218:221], v[66:69]
	v_mfma_f32_16x16x32_bf16 v[70:73], v[146:149], v[218:221], v[70:73]
	v_mfma_f32_16x16x32_bf16 v[118:121], v[150:153], v[188:191], v[118:121]
	v_mfma_f32_16x16x32_bf16 v[114:117], v[180:183], v[188:191], v[114:117]
	v_mfma_f32_16x16x32_bf16 v[98:101], v[180:183], v[196:199], v[98:101]
	v_mfma_f32_16x16x32_bf16 v[102:105], v[150:153], v[196:199], v[102:105]
	v_mfma_f32_16x16x32_bf16 v[86:89], v[150:153], v[214:217], v[86:89]
	v_mfma_f32_16x16x32_bf16 v[82:85], v[180:183], v[214:217], v[82:85]
	v_mfma_f32_16x16x32_bf16 v[66:69], v[180:183], v[222:225], v[66:69]
	v_mfma_f32_16x16x32_bf16 v[70:73], v[150:153], v[222:225], v[70:73]
	s_setprio 0
	s_barrier
	s_add_i32 s67, s62, s52
	s_mov_b32 m0, s67
	ds_read_b128 v[184:187], v208 offset:16384
	ds_read_b128 v[188:191], v208 offset:17408
	ds_read_b128 v[192:195], v208 offset:18432
	ds_read_b128 v[196:199], v208 offset:19456
	ds_read_b128 v[210:213], v208 offset:20480
	ds_read_b128 v[214:217], v208 offset:21504
	ds_read_b128 v[218:221], v208 offset:22528
	ds_read_b128 v[222:225], v208 offset:23552
	global_load_lds_dwordx4 v156, s[44:45]
	s_add_i32 m0, s67, 0x2000
	s_add_u32 s68, s44, 0x400000
	s_addc_u32 s69, s45, 0
	s_add_i32 s67, s63, s52
	global_load_lds_dwordx4 v160, s[44:45]
	s_mov_b32 m0, s67
	s_nop 0
	global_load_lds_dwordx4 v156, s[68:69]
	s_add_i32 m0, s67, 0x2000
	s_nop 0
	global_load_lds_dwordx4 v160, s[68:69]
	s_mov_b32 m0, s53
	s_nop 0
	global_load_lds_dwordx4 v154, s[46:47]
	s_mov_b32 m0, s54
	s_nop 0
	global_load_lds_dwordx4 v158, s[46:47]
	s_waitcnt vmcnt(8)
	s_waitcnt lgkmcnt(0)
	s_barrier
	s_setprio 1
	s_waitcnt lgkmcnt(0)
	v_mfma_f32_16x16x32_bf16 v[62:65], v[130:133], v[184:187], v[62:65]
	v_mfma_f32_16x16x32_bf16 v[58:61], v[138:141], v[184:187], v[58:61]
	v_mfma_f32_16x16x32_bf16 v[42:45], v[138:141], v[192:195], v[42:45]
	v_mfma_f32_16x16x32_bf16 v[46:49], v[130:133], v[192:195], v[46:49]
	v_mfma_f32_16x16x32_bf16 v[30:33], v[130:133], v[210:213], v[30:33]
	v_mfma_f32_16x16x32_bf16 v[26:29], v[138:141], v[210:213], v[26:29]
	v_mfma_f32_16x16x32_bf16 v[10:13], v[138:141], v[218:221], v[10:13]
	v_mfma_f32_16x16x32_bf16 v[14:17], v[130:133], v[218:221], v[14:17]
	v_mfma_f32_16x16x32_bf16 v[62:65], v[134:137], v[188:191], v[62:65]
	v_mfma_f32_16x16x32_bf16 v[58:61], v[142:145], v[188:191], v[58:61]
	v_mfma_f32_16x16x32_bf16 v[42:45], v[142:145], v[196:199], v[42:45]
	v_mfma_f32_16x16x32_bf16 v[46:49], v[134:137], v[196:199], v[46:49]
	v_mfma_f32_16x16x32_bf16 v[30:33], v[134:137], v[214:217], v[30:33]
	v_mfma_f32_16x16x32_bf16 v[26:29], v[142:145], v[214:217], v[26:29]
	v_mfma_f32_16x16x32_bf16 v[10:13], v[142:145], v[222:225], v[10:13]
	v_mfma_f32_16x16x32_bf16 v[14:17], v[134:137], v[222:225], v[14:17]
	s_setprio 0
	s_setprio 1
	v_mfma_f32_16x16x32_bf16 v[54:57], v[146:149], v[184:187], v[54:57]
	v_mfma_f32_16x16x32_bf16 v[50:53], v[176:179], v[184:187], v[50:53]
	v_mfma_f32_16x16x32_bf16 v[34:37], v[176:179], v[192:195], v[34:37]
	v_mfma_f32_16x16x32_bf16 v[38:41], v[146:149], v[192:195], v[38:41]
	v_mfma_f32_16x16x32_bf16 v[22:25], v[146:149], v[210:213], v[22:25]
	v_mfma_f32_16x16x32_bf16 v[18:21], v[176:179], v[210:213], v[18:21]
	v_mfma_f32_16x16x32_bf16 v[2:5], v[176:179], v[218:221], v[2:5]
	v_mfma_f32_16x16x32_bf16 v[6:9], v[146:149], v[218:221], v[6:9]
	v_mfma_f32_16x16x32_bf16 v[54:57], v[150:153], v[188:191], v[54:57]
	v_mfma_f32_16x16x32_bf16 v[50:53], v[180:183], v[188:191], v[50:53]
	v_mfma_f32_16x16x32_bf16 v[34:37], v[180:183], v[196:199], v[34:37]
	v_mfma_f32_16x16x32_bf16 v[38:41], v[150:153], v[196:199], v[38:41]
	v_mfma_f32_16x16x32_bf16 v[22:25], v[150:153], v[214:217], v[22:25]
	v_mfma_f32_16x16x32_bf16 v[18:21], v[180:183], v[214:217], v[18:21]
	v_mfma_f32_16x16x32_bf16 v[2:5], v[180:183], v[222:225], v[2:5]
	v_mfma_f32_16x16x32_bf16 v[6:9], v[150:153], v[222:225], v[6:9]
	s_setprio 0
	s_barrier
	s_add_i32 s67, 0, 0x18000
	s_add_i32 s68, 0, 0x1c000
	v_add_u32_e32 v142, s67, v203
	v_add_u32_e32 v162, s68, v203
	ds_read_b128 v[130:133], v142
	ds_read_b128 v[134:137], v142 offset:1024
	ds_read_b128 v[138:141], v142 offset:2048
	ds_read_b128 v[142:145], v142 offset:3072
	ds_read_b128 v[146:149], v162
	ds_read_b128 v[150:153], v162 offset:1024
	ds_read_b128 v[176:179], v162 offset:2048
	ds_read_b128 v[180:183], v162 offset:3072
	s_add_u32 s46, s46, 0x400000
	s_addc_u32 s47, s47, 0
	s_mov_b32 m0, s55
	ds_read_b128 v[184:187], v208 offset:32768
	ds_read_b128 v[188:191], v208 offset:33792
	ds_read_b128 v[192:195], v208 offset:34816
	ds_read_b128 v[196:199], v208 offset:35840
	ds_read_b128 v[210:213], v208 offset:36864
	ds_read_b128 v[214:217], v208 offset:37888
	ds_read_b128 v[218:221], v208 offset:38912
	ds_read_b128 v[222:225], v208 offset:39936
	global_load_lds_dwordx4 v154, s[46:47]
	s_mov_b32 m0, s56
	s_nop 0
	global_load_lds_dwordx4 v158, s[46:47]
	s_waitcnt vmcnt(8)
	s_waitcnt lgkmcnt(0)
	s_barrier
	s_setprio 1
	s_waitcnt lgkmcnt(0)
	v_mfma_f32_16x16x32_bf16 v[126:129], v[130:133], v[184:187], v[126:129]
	v_mfma_f32_16x16x32_bf16 v[122:125], v[138:141], v[184:187], v[122:125]
	v_mfma_f32_16x16x32_bf16 v[106:109], v[138:141], v[192:195], v[106:109]
	v_mfma_f32_16x16x32_bf16 v[110:113], v[130:133], v[192:195], v[110:113]
	v_mfma_f32_16x16x32_bf16 v[94:97], v[130:133], v[210:213], v[94:97]
	v_mfma_f32_16x16x32_bf16 v[90:93], v[138:141], v[210:213], v[90:93]
	v_mfma_f32_16x16x32_bf16 v[74:77], v[138:141], v[218:221], v[74:77]
	v_mfma_f32_16x16x32_bf16 v[78:81], v[130:133], v[218:221], v[78:81]
	v_mfma_f32_16x16x32_bf16 v[126:129], v[134:137], v[188:191], v[126:129]
	v_mfma_f32_16x16x32_bf16 v[122:125], v[142:145], v[188:191], v[122:125]
	v_mfma_f32_16x16x32_bf16 v[106:109], v[142:145], v[196:199], v[106:109]
	v_mfma_f32_16x16x32_bf16 v[110:113], v[134:137], v[196:199], v[110:113]
	v_mfma_f32_16x16x32_bf16 v[94:97], v[134:137], v[214:217], v[94:97]
	v_mfma_f32_16x16x32_bf16 v[90:93], v[142:145], v[214:217], v[90:93]
	v_mfma_f32_16x16x32_bf16 v[74:77], v[142:145], v[222:225], v[74:77]
	v_mfma_f32_16x16x32_bf16 v[78:81], v[134:137], v[222:225], v[78:81]
	s_setprio 0
	s_setprio 1
	v_mfma_f32_16x16x32_bf16 v[118:121], v[146:149], v[184:187], v[118:121]
	v_mfma_f32_16x16x32_bf16 v[114:117], v[176:179], v[184:187], v[114:117]
	v_mfma_f32_16x16x32_bf16 v[98:101], v[176:179], v[192:195], v[98:101]
	v_mfma_f32_16x16x32_bf16 v[102:105], v[146:149], v[192:195], v[102:105]
	v_mfma_f32_16x16x32_bf16 v[86:89], v[146:149], v[210:213], v[86:89]
	v_mfma_f32_16x16x32_bf16 v[82:85], v[176:179], v[210:213], v[82:85]
	v_mfma_f32_16x16x32_bf16 v[66:69], v[176:179], v[218:221], v[66:69]
	v_mfma_f32_16x16x32_bf16 v[70:73], v[146:149], v[218:221], v[70:73]
	v_mfma_f32_16x16x32_bf16 v[118:121], v[150:153], v[188:191], v[118:121]
	v_mfma_f32_16x16x32_bf16 v[114:117], v[180:183], v[188:191], v[114:117]
	v_mfma_f32_16x16x32_bf16 v[98:101], v[180:183], v[196:199], v[98:101]
	v_mfma_f32_16x16x32_bf16 v[102:105], v[150:153], v[196:199], v[102:105]
	v_mfma_f32_16x16x32_bf16 v[86:89], v[150:153], v[214:217], v[86:89]
	v_mfma_f32_16x16x32_bf16 v[82:85], v[180:183], v[214:217], v[82:85]
	v_mfma_f32_16x16x32_bf16 v[66:69], v[180:183], v[222:225], v[66:69]
	v_mfma_f32_16x16x32_bf16 v[70:73], v[150:153], v[222:225], v[70:73]
	s_setprio 0
	s_barrier
	s_add_u32 s46, s44, 0x4000
	s_addc_u32 s47, s45, 0
	s_add_i32 s67, s67, s52
	s_mov_b32 m0, s67
	ds_read_b128 v[184:187], v208 offset:49152
	ds_read_b128 v[188:191], v208 offset:50176
	ds_read_b128 v[192:195], v208 offset:51200
	ds_read_b128 v[196:199], v208 offset:52224
	ds_read_b128 v[210:213], v208 offset:53248
	ds_read_b128 v[214:217], v208 offset:54272
	ds_read_b128 v[218:221], v208 offset:55296
	ds_read_b128 v[222:225], v208 offset:56320
	global_load_lds_dwordx4 v156, s[46:47]
	s_add_i32 m0, s67, 0x2000
	s_add_u32 s44, s44, 0x404000
	s_addc_u32 s45, s45, 0
	global_load_lds_dwordx4 v160, s[46:47]
	s_add_i32 s46, s68, s52
	s_mov_b32 m0, s46
	s_nop 0
	global_load_lds_dwordx4 v156, s[44:45]
	s_add_i32 m0, s46, 0x2000
	s_nop 0
	global_load_lds_dwordx4 v160, s[44:45]
	s_mov_b32 m0, s60
	s_nop 0
	global_load_lds_dwordx4 v154, s[42:43]
	s_mov_b32 m0, s61
	s_nop 0
	global_load_lds_dwordx4 v158, s[42:43]
	s_waitcnt vmcnt(8)
	s_waitcnt lgkmcnt(0)
	s_barrier
	s_setprio 1
	s_waitcnt lgkmcnt(0)
	v_mfma_f32_16x16x32_bf16 v[62:65], v[130:133], v[184:187], v[62:65]
	v_mfma_f32_16x16x32_bf16 v[58:61], v[138:141], v[184:187], v[58:61]
	v_mfma_f32_16x16x32_bf16 v[42:45], v[138:141], v[192:195], v[42:45]
	v_mfma_f32_16x16x32_bf16 v[46:49], v[130:133], v[192:195], v[46:49]
	v_mfma_f32_16x16x32_bf16 v[30:33], v[130:133], v[210:213], v[30:33]
	v_mfma_f32_16x16x32_bf16 v[26:29], v[138:141], v[210:213], v[26:29]
	v_mfma_f32_16x16x32_bf16 v[10:13], v[138:141], v[218:221], v[10:13]
	v_mfma_f32_16x16x32_bf16 v[14:17], v[130:133], v[218:221], v[14:17]
	v_mfma_f32_16x16x32_bf16 v[62:65], v[134:137], v[188:191], v[62:65]
	v_mfma_f32_16x16x32_bf16 v[58:61], v[142:145], v[188:191], v[58:61]
	v_mfma_f32_16x16x32_bf16 v[42:45], v[142:145], v[196:199], v[42:45]
	v_mfma_f32_16x16x32_bf16 v[46:49], v[134:137], v[196:199], v[46:49]
	v_mfma_f32_16x16x32_bf16 v[30:33], v[134:137], v[214:217], v[30:33]
	v_mfma_f32_16x16x32_bf16 v[26:29], v[142:145], v[214:217], v[26:29]
	v_mfma_f32_16x16x32_bf16 v[10:13], v[142:145], v[222:225], v[10:13]
	v_mfma_f32_16x16x32_bf16 v[14:17], v[134:137], v[222:225], v[14:17]
	s_setprio 0
	s_setprio 1
	v_mfma_f32_16x16x32_bf16 v[54:57], v[146:149], v[184:187], v[54:57]
	v_mfma_f32_16x16x32_bf16 v[50:53], v[176:179], v[184:187], v[50:53]
	v_mfma_f32_16x16x32_bf16 v[34:37], v[176:179], v[192:195], v[34:37]
	v_mfma_f32_16x16x32_bf16 v[38:41], v[146:149], v[192:195], v[38:41]
	v_mfma_f32_16x16x32_bf16 v[22:25], v[146:149], v[210:213], v[22:25]
	v_mfma_f32_16x16x32_bf16 v[18:21], v[176:179], v[210:213], v[18:21]
	v_mfma_f32_16x16x32_bf16 v[2:5], v[176:179], v[218:221], v[2:5]
	v_mfma_f32_16x16x32_bf16 v[6:9], v[146:149], v[218:221], v[6:9]
	v_mfma_f32_16x16x32_bf16 v[54:57], v[150:153], v[188:191], v[54:57]
	v_mfma_f32_16x16x32_bf16 v[50:53], v[180:183], v[188:191], v[50:53]
	v_mfma_f32_16x16x32_bf16 v[34:37], v[180:183], v[196:199], v[34:37]
	v_mfma_f32_16x16x32_bf16 v[38:41], v[150:153], v[196:199], v[38:41]
	v_mfma_f32_16x16x32_bf16 v[22:25], v[150:153], v[214:217], v[22:25]
	v_mfma_f32_16x16x32_bf16 v[18:21], v[180:183], v[214:217], v[18:21]
	v_mfma_f32_16x16x32_bf16 v[2:5], v[180:183], v[222:225], v[2:5]
	v_mfma_f32_16x16x32_bf16 v[6:9], v[150:153], v[222:225], v[6:9]
	s_setprio 0
	s_barrier
	s_add_i32 s66, s66, 2
	s_add_u32 s40, s40, 0x8000
	s_addc_u32 s41, s41, 0
	s_add_u32 s39, s39, 0x8000
	s_addc_u32 s65, s65, 0
	s_cmpk_gt_u32 s66, 0xfd
	s_cbranch_scc0 .LBB0_1292
	s_and_b64 vcc, exec, s[24:25]
	s_cbranch_vccz .LBB0_1295
	s_barrier

.LBB0_1387:
	ds_read_b128 v[62:65], v189
	ds_read_b128 v[66:69], v189 offset:1024
	ds_read_b128 v[74:77], v189 offset:2048
	ds_read_b128 v[78:81], v189 offset:3072
	ds_read_b128 v[146:149], v195
	ds_read_b128 v[150:153], v195 offset:1024
	ds_read_b128 v[154:157], v195 offset:2048
	ds_read_b128 v[158:161], v195 offset:3072
	s_add_u32 s34, s30, 0xfff04000
	s_addc_u32 s35, s31, -1
	s_cmp_eq_u32 s54, 60
	s_cselect_b32 s38, s27, s34
	s_cselect_b32 s39, s21, s35
	s_cselect_b32 s36, s29, s52
	s_cselect_b32 s37, s19, s53
	s_add_u32 s34, s38, 0x4000
	s_addc_u32 s35, s39, 0
	s_add_i32 m0, s40, 0xc000
	ds_read_b128 v[190:193], v197
	ds_read_b128 v[198:201], v197 offset:1024
	ds_read_b128 v[202:205], v197 offset:2048
	ds_read_b128 v[206:209], v197 offset:3072
	ds_read_b128 v[210:213], v197 offset:4096
	ds_read_b128 v[214:217], v197 offset:5120
	ds_read_b128 v[218:221], v197 offset:6144
	ds_read_b128 v[222:225], v197 offset:7168
	global_load_lds_dwordx4 v172, s[30:31]
	s_add_i32 m0, s40, 0xe000
	s_nop 0
	global_load_lds_dwordx4 v174, s[30:31]
	s_waitcnt vmcnt(8)
	s_waitcnt lgkmcnt(0)
	s_barrier
	s_setprio 1
	s_waitcnt lgkmcnt(0)
	v_mfma_f32_16x16x32_bf16 v[142:145], v[62:65], v[190:193], v[142:145]
	v_mfma_f32_16x16x32_bf16 v[138:141], v[74:77], v[190:193], v[138:141]
	v_mfma_f32_16x16x32_bf16 v[122:125], v[74:77], v[202:205], v[122:125]
	v_mfma_f32_16x16x32_bf16 v[126:129], v[62:65], v[202:205], v[126:129]
	v_mfma_f32_16x16x32_bf16 v[110:113], v[62:65], v[210:213], v[110:113]
	v_mfma_f32_16x16x32_bf16 v[106:109], v[74:77], v[210:213], v[106:109]
	v_mfma_f32_16x16x32_bf16 v[90:93], v[74:77], v[218:221], v[90:93]
	v_mfma_f32_16x16x32_bf16 v[94:97], v[62:65], v[218:221], v[94:97]
	v_mfma_f32_16x16x32_bf16 v[142:145], v[66:69], v[198:201], v[142:145]
	v_mfma_f32_16x16x32_bf16 v[138:141], v[78:81], v[198:201], v[138:141]
	v_mfma_f32_16x16x32_bf16 v[122:125], v[78:81], v[206:209], v[122:125]
	v_mfma_f32_16x16x32_bf16 v[126:129], v[66:69], v[206:209], v[126:129]
	v_mfma_f32_16x16x32_bf16 v[110:113], v[66:69], v[214:217], v[110:113]
	v_mfma_f32_16x16x32_bf16 v[106:109], v[78:81], v[214:217], v[106:109]
	v_mfma_f32_16x16x32_bf16 v[90:93], v[78:81], v[222:225], v[90:93]
	v_mfma_f32_16x16x32_bf16 v[94:97], v[66:69], v[222:225], v[94:97]
	s_setprio 0
	s_setprio 1
	v_mfma_f32_16x16x32_bf16 v[134:137], v[146:149], v[190:193], v[134:137]
	v_mfma_f32_16x16x32_bf16 v[130:133], v[154:157], v[190:193], v[130:133]
	v_mfma_f32_16x16x32_bf16 v[114:117], v[154:157], v[202:205], v[114:117]
	v_mfma_f32_16x16x32_bf16 v[118:121], v[146:149], v[202:205], v[118:121]
	v_mfma_f32_16x16x32_bf16 v[102:105], v[146:149], v[210:213], v[102:105]
	v_mfma_f32_16x16x32_bf16 v[98:101], v[154:157], v[210:213], v[98:101]
	v_mfma_f32_16x16x32_bf16 v[82:85], v[154:157], v[218:221], v[82:85]
	v_mfma_f32_16x16x32_bf16 v[86:89], v[146:149], v[218:221], v[86:89]
	v_mfma_f32_16x16x32_bf16 v[134:137], v[150:153], v[198:201], v[134:137]
	v_mfma_f32_16x16x32_bf16 v[130:133], v[158:161], v[198:201], v[130:133]
	v_mfma_f32_16x16x32_bf16 v[114:117], v[158:161], v[206:209], v[114:117]
	v_mfma_f32_16x16x32_bf16 v[118:121], v[150:153], v[206:209], v[118:121]
	v_mfma_f32_16x16x32_bf16 v[102:105], v[150:153], v[214:217], v[102:105]
	v_mfma_f32_16x16x32_bf16 v[98:101], v[158:161], v[214:217], v[98:101]
	v_mfma_f32_16x16x32_bf16 v[82:85], v[158:161], v[222:225], v[82:85]
	v_mfma_f32_16x16x32_bf16 v[86:89], v[150:153], v[222:225], v[86:89]
	s_setprio 0
	s_barrier
	s_add_i32 s55, s50, s33
	s_mov_b32 m0, s55
	ds_read_b128 v[190:193], v197 offset:16384
	ds_read_b128 v[198:201], v197 offset:17408
	ds_read_b128 v[202:205], v197 offset:18432
	ds_read_b128 v[206:209], v197 offset:19456
	ds_read_b128 v[210:213], v197 offset:20480
	ds_read_b128 v[214:217], v197 offset:21504
	ds_read_b128 v[218:221], v197 offset:22528
	ds_read_b128 v[222:225], v197 offset:23552
	global_load_lds_dwordx4 v166, s[36:37]
	s_add_i32 m0, s55, 0x2000
	s_add_u32 s56, s36, 0x100000
	s_addc_u32 s57, s37, 0
	s_add_i32 s55, s51, s33
	global_load_lds_dwordx4 v162, s[36:37]
	s_mov_b32 m0, s55
	s_nop 0
	global_load_lds_dwordx4 v166, s[56:57]
	s_add_i32 m0, s55, 0x2000
	s_nop 0
	global_load_lds_dwordx4 v162, s[56:57]
	s_mov_b32 m0, s40
	s_nop 0
	global_load_lds_dwordx4 v168, s[38:39]
	s_mov_b32 m0, s41
	s_nop 0
	global_load_lds_dwordx4 v164, s[38:39]
	s_waitcnt vmcnt(8)
	s_waitcnt lgkmcnt(0)
	s_barrier
	s_setprio 1
	s_waitcnt lgkmcnt(0)
	v_mfma_f32_16x16x32_bf16 v[70:73], v[62:65], v[190:193], v[70:73]
	v_mfma_f32_16x16x32_bf16 v[58:61], v[74:77], v[190:193], v[58:61]
	v_mfma_f32_16x16x32_bf16 v[42:45], v[74:77], v[202:205], v[42:45]
	v_mfma_f32_16x16x32_bf16 v[46:49], v[62:65], v[202:205], v[46:49]
	v_mfma_f32_16x16x32_bf16 v[30:33], v[62:65], v[210:213], v[30:33]
	v_mfma_f32_16x16x32_bf16 v[26:29], v[74:77], v[210:213], v[26:29]
	v_mfma_f32_16x16x32_bf16 v[10:13], v[74:77], v[218:221], v[10:13]
	v_mfma_f32_16x16x32_bf16 v[14:17], v[62:65], v[218:221], v[14:17]
	v_mfma_f32_16x16x32_bf16 v[70:73], v[66:69], v[198:201], v[70:73]
	v_mfma_f32_16x16x32_bf16 v[58:61], v[78:81], v[198:201], v[58:61]
	v_mfma_f32_16x16x32_bf16 v[42:45], v[78:81], v[206:209], v[42:45]
	v_mfma_f32_16x16x32_bf16 v[46:49], v[66:69], v[206:209], v[46:49]
	v_mfma_f32_16x16x32_bf16 v[30:33], v[66:69], v[214:217], v[30:33]
	v_mfma_f32_16x16x32_bf16 v[26:29], v[78:81], v[214:217], v[26:29]
	v_mfma_f32_16x16x32_bf16 v[10:13], v[78:81], v[222:225], v[10:13]
	v_mfma_f32_16x16x32_bf16 v[14:17], v[66:69], v[222:225], v[14:17]
	s_setprio 0
	s_setprio 1
	v_mfma_f32_16x16x32_bf16 v[54:57], v[146:149], v[190:193], v[54:57]
	v_mfma_f32_16x16x32_bf16 v[50:53], v[154:157], v[190:193], v[50:53]
	v_mfma_f32_16x16x32_bf16 v[34:37], v[154:157], v[202:205], v[34:37]
	v_mfma_f32_16x16x32_bf16 v[38:41], v[146:149], v[202:205], v[38:41]
	v_mfma_f32_16x16x32_bf16 v[22:25], v[146:149], v[210:213], v[22:25]
	v_mfma_f32_16x16x32_bf16 v[18:21], v[154:157], v[210:213], v[18:21]
	v_mfma_f32_16x16x32_bf16 v[2:5], v[154:157], v[218:221], v[2:5]
	v_mfma_f32_16x16x32_bf16 v[6:9], v[146:149], v[218:221], v[6:9]
	v_mfma_f32_16x16x32_bf16 v[54:57], v[150:153], v[198:201], v[54:57]
	v_mfma_f32_16x16x32_bf16 v[50:53], v[158:161], v[198:201], v[50:53]
	v_mfma_f32_16x16x32_bf16 v[34:37], v[158:161], v[206:209], v[34:37]
	v_mfma_f32_16x16x32_bf16 v[38:41], v[150:153], v[206:209], v[38:41]
	v_mfma_f32_16x16x32_bf16 v[22:25], v[150:153], v[214:217], v[22:25]
	v_mfma_f32_16x16x32_bf16 v[18:21], v[158:161], v[214:217], v[18:21]
	v_mfma_f32_16x16x32_bf16 v[2:5], v[158:161], v[222:225], v[2:5]
	v_mfma_f32_16x16x32_bf16 v[6:9], v[150:153], v[222:225], v[6:9]
	s_setprio 0
	s_barrier
	s_add_i32 s55, 0, 0x18000
	s_add_i32 s56, 0, 0x1c000
	v_add_u32_e32 v78, s55, v187
	v_add_u32_e32 v158, s56, v187
	ds_read_b128 v[62:65], v78
	ds_read_b128 v[66:69], v78 offset:1024
	ds_read_b128 v[74:77], v78 offset:2048
	ds_read_b128 v[78:81], v78 offset:3072
	ds_read_b128 v[146:149], v158
	ds_read_b128 v[150:153], v158 offset:1024
	ds_read_b128 v[154:157], v158 offset:2048
	ds_read_b128 v[158:161], v158 offset:3072
	s_add_u32 s38, s38, 0x100000
	s_addc_u32 s39, s39, 0
	s_mov_b32 m0, s42
	ds_read_b128 v[190:193], v197 offset:32768
	ds_read_b128 v[198:201], v197 offset:33792
	ds_read_b128 v[202:205], v197 offset:34816
	ds_read_b128 v[206:209], v197 offset:35840
	ds_read_b128 v[210:213], v197 offset:36864
	ds_read_b128 v[214:217], v197 offset:37888
	ds_read_b128 v[218:221], v197 offset:38912
	ds_read_b128 v[222:225], v197 offset:39936
	global_load_lds_dwordx4 v168, s[38:39]
	s_mov_b32 m0, s43
	s_nop 0
	global_load_lds_dwordx4 v164, s[38:39]
	s_waitcnt vmcnt(8)
	s_waitcnt lgkmcnt(0)
	s_barrier
	s_setprio 1
	s_waitcnt lgkmcnt(0)
	v_mfma_f32_16x16x32_bf16 v[142:145], v[62:65], v[190:193], v[142:145]
	v_mfma_f32_16x16x32_bf16 v[138:141], v[74:77], v[190:193], v[138:141]
	v_mfma_f32_16x16x32_bf16 v[122:125], v[74:77], v[202:205], v[122:125]
	v_mfma_f32_16x16x32_bf16 v[126:129], v[62:65], v[202:205], v[126:129]
	v_mfma_f32_16x16x32_bf16 v[110:113], v[62:65], v[210:213], v[110:113]
	v_mfma_f32_16x16x32_bf16 v[106:109], v[74:77], v[210:213], v[106:109]
	v_mfma_f32_16x16x32_bf16 v[90:93], v[74:77], v[218:221], v[90:93]
	v_mfma_f32_16x16x32_bf16 v[94:97], v[62:65], v[218:221], v[94:97]
	v_mfma_f32_16x16x32_bf16 v[142:145], v[66:69], v[198:201], v[142:145]
	v_mfma_f32_16x16x32_bf16 v[138:141], v[78:81], v[198:201], v[138:141]
	v_mfma_f32_16x16x32_bf16 v[122:125], v[78:81], v[206:209], v[122:125]
	v_mfma_f32_16x16x32_bf16 v[126:129], v[66:69], v[206:209], v[126:129]
	v_mfma_f32_16x16x32_bf16 v[110:113], v[66:69], v[214:217], v[110:113]
	v_mfma_f32_16x16x32_bf16 v[106:109], v[78:81], v[214:217], v[106:109]
	v_mfma_f32_16x16x32_bf16 v[90:93], v[78:81], v[222:225], v[90:93]
	v_mfma_f32_16x16x32_bf16 v[94:97], v[66:69], v[222:225], v[94:97]
	s_setprio 0
	s_setprio 1
	v_mfma_f32_16x16x32_bf16 v[134:137], v[146:149], v[190:193], v[134:137]
	v_mfma_f32_16x16x32_bf16 v[130:133], v[154:157], v[190:193], v[130:133]
	v_mfma_f32_16x16x32_bf16 v[114:117], v[154:157], v[202:205], v[114:117]
	v_mfma_f32_16x16x32_bf16 v[118:121], v[146:149], v[202:205], v[118:121]
	v_mfma_f32_16x16x32_bf16 v[102:105], v[146:149], v[210:213], v[102:105]
	v_mfma_f32_16x16x32_bf16 v[98:101], v[154:157], v[210:213], v[98:101]
	v_mfma_f32_16x16x32_bf16 v[82:85], v[154:157], v[218:221], v[82:85]
	v_mfma_f32_16x16x32_bf16 v[86:89], v[146:149], v[218:221], v[86:89]
	v_mfma_f32_16x16x32_bf16 v[134:137], v[150:153], v[198:201], v[134:137]
	v_mfma_f32_16x16x32_bf16 v[130:133], v[158:161], v[198:201], v[130:133]
	v_mfma_f32_16x16x32_bf16 v[114:117], v[158:161], v[206:209], v[114:117]
	v_mfma_f32_16x16x32_bf16 v[118:121], v[150:153], v[206:209], v[118:121]
	v_mfma_f32_16x16x32_bf16 v[102:105], v[150:153], v[214:217], v[102:105]
	v_mfma_f32_16x16x32_bf16 v[98:101], v[158:161], v[214:217], v[98:101]
	v_mfma_f32_16x16x32_bf16 v[82:85], v[158:161], v[222:225], v[82:85]
	v_mfma_f32_16x16x32_bf16 v[86:89], v[150:153], v[222:225], v[86:89]
	s_setprio 0
	s_barrier
	s_add_u32 s38, s36, 0x4000
	s_addc_u32 s39, s37, 0
	s_add_i32 s55, s55, s33
	s_mov_b32 m0, s55
	ds_read_b128 v[190:193], v197 offset:49152
	ds_read_b128 v[198:201], v197 offset:50176
	ds_read_b128 v[202:205], v197 offset:51200
	ds_read_b128 v[206:209], v197 offset:52224
	ds_read_b128 v[210:213], v197 offset:53248
	ds_read_b128 v[214:217], v197 offset:54272
	ds_read_b128 v[218:221], v197 offset:55296
	ds_read_b128 v[222:225], v197 offset:56320
	global_load_lds_dwordx4 v166, s[38:39]
	s_add_i32 m0, s55, 0x2000
	s_add_u32 s36, s36, 0x104000
	s_addc_u32 s37, s37, 0
	global_load_lds_dwordx4 v162, s[38:39]
	s_add_i32 s38, s56, s33
	s_mov_b32 m0, s38
	s_nop 0
	global_load_lds_dwordx4 v166, s[36:37]
	s_add_i32 m0, s38, 0x2000
	s_nop 0
	global_load_lds_dwordx4 v162, s[36:37]
	s_mov_b32 m0, s46
	s_nop 0
	global_load_lds_dwordx4 v168, s[34:35]
	s_mov_b32 m0, s47
	s_nop 0
	global_load_lds_dwordx4 v164, s[34:35]
	s_waitcnt vmcnt(8)
	s_waitcnt lgkmcnt(0)
	s_barrier
	s_setprio 1
	s_waitcnt lgkmcnt(0)
	v_mfma_f32_16x16x32_bf16 v[70:73], v[62:65], v[190:193], v[70:73]
	v_mfma_f32_16x16x32_bf16 v[58:61], v[74:77], v[190:193], v[58:61]
	v_mfma_f32_16x16x32_bf16 v[42:45], v[74:77], v[202:205], v[42:45]
	v_mfma_f32_16x16x32_bf16 v[46:49], v[62:65], v[202:205], v[46:49]
	v_mfma_f32_16x16x32_bf16 v[30:33], v[62:65], v[210:213], v[30:33]
	v_mfma_f32_16x16x32_bf16 v[26:29], v[74:77], v[210:213], v[26:29]
	v_mfma_f32_16x16x32_bf16 v[10:13], v[74:77], v[218:221], v[10:13]
	v_mfma_f32_16x16x32_bf16 v[14:17], v[62:65], v[218:221], v[14:17]
	v_mfma_f32_16x16x32_bf16 v[70:73], v[66:69], v[198:201], v[70:73]
	v_mfma_f32_16x16x32_bf16 v[58:61], v[78:81], v[198:201], v[58:61]
	v_mfma_f32_16x16x32_bf16 v[42:45], v[78:81], v[206:209], v[42:45]
	v_mfma_f32_16x16x32_bf16 v[46:49], v[66:69], v[206:209], v[46:49]
	v_mfma_f32_16x16x32_bf16 v[30:33], v[66:69], v[214:217], v[30:33]
	v_mfma_f32_16x16x32_bf16 v[26:29], v[78:81], v[214:217], v[26:29]
	v_mfma_f32_16x16x32_bf16 v[10:13], v[78:81], v[222:225], v[10:13]
	v_mfma_f32_16x16x32_bf16 v[14:17], v[66:69], v[222:225], v[14:17]
	s_setprio 0
	s_setprio 1
	v_mfma_f32_16x16x32_bf16 v[54:57], v[146:149], v[190:193], v[54:57]
	v_mfma_f32_16x16x32_bf16 v[50:53], v[154:157], v[190:193], v[50:53]
	v_mfma_f32_16x16x32_bf16 v[34:37], v[154:157], v[202:205], v[34:37]
	v_mfma_f32_16x16x32_bf16 v[38:41], v[146:149], v[202:205], v[38:41]
	v_mfma_f32_16x16x32_bf16 v[22:25], v[146:149], v[210:213], v[22:25]
	v_mfma_f32_16x16x32_bf16 v[18:21], v[154:157], v[210:213], v[18:21]
	v_mfma_f32_16x16x32_bf16 v[2:5], v[154:157], v[218:221], v[2:5]
	v_mfma_f32_16x16x32_bf16 v[6:9], v[146:149], v[218:221], v[6:9]
	v_mfma_f32_16x16x32_bf16 v[54:57], v[150:153], v[198:201], v[54:57]
	v_mfma_f32_16x16x32_bf16 v[50:53], v[158:161], v[198:201], v[50:53]
	v_mfma_f32_16x16x32_bf16 v[34:37], v[158:161], v[206:209], v[34:37]
	v_mfma_f32_16x16x32_bf16 v[38:41], v[150:153], v[206:209], v[38:41]
	v_mfma_f32_16x16x32_bf16 v[22:25], v[150:153], v[214:217], v[22:25]
	v_mfma_f32_16x16x32_bf16 v[18:21], v[158:161], v[214:217], v[18:21]
	v_mfma_f32_16x16x32_bf16 v[2:5], v[158:161], v[222:225], v[2:5]
	v_mfma_f32_16x16x32_bf16 v[6:9], v[150:153], v[222:225], v[6:9]
	s_setprio 0
	s_barrier
	s_add_i32 s54, s54, 2
	s_add_u32 s30, s30, 0x8000
	s_addc_u32 s31, s31, 0
	s_add_u32 s52, s52, 0x8000
	s_addc_u32 s53, s53, 0
	s_cmp_gt_u32 s54, 61
	s_cbranch_scc0 .LBB0_1387
	s_and_b64 vcc, exec, s[12:13]
	s_cbranch_vccz .LBB0_1390
	s_barrier
